# v47 with hipcc per-segment s_setprio flips removed and one static s_setprio 1 for the younger wave half (waves 4-7) in the three GEMM phases
# speedup vs baseline: 1.0018x; 1.0018x over previous
; DI int opaque_tid() { int t = threadIdx.x; asm volatile("" : "+v"(t)); return t; }
; #define PG8_STAGE(bufoff, gbase, voff) do { _Pragma("unroll") for (int _i = 0; _i < 2; ++_i) \
;         __builtin_amdgcn_global_load_lds((const unsigned*)((const char*)(gbase) + (voff)[_i]), (LAS unsigned*)(lds + (bufoff) + ldsw + _i * 8192), 16, 0, 0); } while (0)
; #define PG8_BAR __builtin_amdgcn_s_barrier()
; template <class Epi>
; DI void gemm_phase(LAS unsigned char* lds, const Gemm g, const Order& S, const Epi& E) {
;     const int tid = opaque_tid(), wid = __builtin_amdgcn_readfirstlane(tid >> 6), lane = tid & 63, wr = wid >> 2, wc = wid & 3, fr = lane & 15, fq = lane >> 4;
;     const int K = g.K, nt = K / BK;
;     unsigned voffA[2], voffB[2];
; #pragma unroll
;     for (int i = 0; i < 2; ++i) { int R, C; stage_rc(tid * 16 + i * 8192, R, C); const int Rb = Epi::PERM ? ((R & ~31) + perm32(R & 31)) : R;
;         voffA[i] = (unsigned)(R * K + C) * 2u; voffB[i] = (unsigned)(Rb * K + C) * 2u; }
;     const size_t kstep = (size_t)(BK * 2);
;     const size_t hstep = (size_t)HALF * K * 2;
;     const size_t tstep = 2 * hstep;
;     const unsigned ldsw = (unsigned)wid * 1024u;
;     const int aoff = lds_byte(wr * 64 + fr, fq * 8), boff = lds_byte(wc * 32 + fr, fq * 8);
;     ...
;     Unit cur, nxt; int ui = 0;
;     if (!S.next(0, cur)) return;
;     f32x4 acc[2][2][4][2];
; #pragma unroll
;     for (int a = 0; a < 2; ++a)
; #pragma unroll
;         for (int b = 0; b < 2; ++b)
; #pragma unroll
;             for (int m = 0; m < 4; ++m)
; #pragma unroll
;                 for (int n = 0; n < 2; ++n) acc[a][b][m][n] = (f32x4){0.f, 0.f, 0.f, 0.f};
;     bf16x8 At[4][2], B0[2][2], B1[2][2];
;     const char* cA = (const char*)(cur.sel ? g.A1 : g.A0) + (size_t)cur.pm * tstep; const char* cB = (const char*)(cur.sel ? g.B1 : g.B0) + (size_t)cur.pn * tstep;
;     PG8_STAGE(PG8_SB(0, 0), cB, voffB); PG8_STAGE(PG8_SB(0, 1), cB + hstep, voffB); PG8_STAGE(PG8_SA(0, 0), cA, voffA); PG8_STAGE(PG8_SA(0, 1), cA + hstep, voffA);
;     if (wr == 1) PG8_BAR;
; __global__ void __launch_bounds__(512, 2) mega(Args a) {
;     ...
;         } else if (k == 4) {
;             pg8::Gemm g{UGf, Hb, (const bf16_t*)(ws + WS_WB), (const bf16_t*)(ws + WS_WA), D};
;             pg8::Order S; S.init(M_ALL, D, G, blk, 1);
;             EpiProjAB E{SMAf, SMBf, out9};
;             pg8::gemm_phase<EpiProjAB>(lds, g, S, E);
.LBB0_87:
	s_lshl_b64 s[0:1], s[0:1], 1
	s_add_u32 s2, s60, s0
	s_addc_u32 s3, s61, s1
	v_writelane_b32 v241, s2, 52
	s_add_u32 s0, s70, s0
	s_addc_u32 s1, s73, s1
	v_writelane_b32 v241, s3, 53
	v_writelane_b32 v241, s0, 54
	s_mov_b64 s[8:9], 0
	s_cmp_lt_i32 s28, 2
	v_writelane_b32 v241, s1, 55
	s_mov_b64 s[0:1], -1
	s_mov_b64 s[36:37], 0
	s_cbranch_scc1 .LBB0_157
	s_cmp_gt_i32 s28, 2
	s_cbranch_scc0 .LBB0_149
	s_cmp_gt_i32 s28, 3
	s_cbranch_scc0 .LBB0_122
	s_cmp_eq_u32 s28, 4
	s_mov_b64 s[36:37], -1
	s_cbranch_scc0 .LBB0_121
	v_readlane_b32 s0, v243, 14
	v_mov_b32_e32 v0, v136
	v_readlane_b32 s1, v243, 15
	s_andn2_b64 vcc, exec, s[0:1]
	v_readfirstlane_b32 s2, v0
	s_cbranch_vccnz .LBB0_120
	v_lshlrev_b32_e32 v4, 4, v0
	v_add_u32_e32 v2, 0x2000, v4
	v_ashrrev_i32_e32 v1, 31, v2
	v_lshrrev_b32_e32 v1, 22, v1
	v_add_u32_e32 v1, v2, v1
	v_ashrrev_i32_e32 v1, 10, v1
	v_mul_i32_i24_e32 v3, 0x400, v1
	v_sub_u32_e32 v2, v2, v3
	v_lshrrev_b32_e32 v3, 4, v2
	v_bitop3_b32 v3, v3, v2, 32 bitop3:0x6c
	v_ashrrev_i32_e32 v2, 31, v3
	v_lshrrev_b32_e32 v2, 26, v2
	v_add_u32_e32 v5, v3, v2
	v_lshlrev_b32_e32 v6, 3, v1
	v_ashrrev_i32_e32 v2, 6, v5
	v_and_b32_e32 v6, -16, v6
	v_add_u32_e32 v6, v2, v6
	v_and_b32_e32 v7, 3, v2
	s_mov_b32 s0, 0x1fffe0
	v_lshrrev_b32_e32 v8, 2, v6
	v_lshlrev_b32_e32 v9, 1, v6
	v_and_b32_e32 v5, 0xc0, v5
	v_and_or_b32 v7, v6, s0, v7
	v_and_b32_e32 v8, 4, v8
	v_and_b32_e32 v9, 24, v9
	v_sub_u32_e32 v3, v3, v5
	v_or3_b32 v7, v7, v8, v9
	v_lshlrev_b32_e32 v8, 5, v1
	v_ashrrev_i16_sdwa v3, v173, sext(v3) dst_sel:DWORD dst_unused:UNUSED_PAD src0_sel:DWORD src1_sel:BYTE_0
	v_and_b32_e32 v8, 32, v8
	v_bfe_i32 v3, v3, 0, 16
	v_add_lshl_u32 v5, v8, v3, 1
	v_lshl_add_u32 v148, v7, 11, v5
	v_lshl_add_u32 v150, v6, 11, v5
	v_bfe_i32 v5, v0, 27, 1
	v_lshrrev_b32_e32 v5, 22, v5
	v_add_u32_e32 v5, v4, v5
	v_and_b32_e32 v5, 0xfffffc00, v5
	v_sub_u32_e32 v4, v4, v5
	v_lshrrev_b32_e32 v5, 4, v4
	v_bitop3_b32 v6, v5, v4, 32 bitop3:0x6c
	v_ashrrev_i32_e32 v5, 31, v0
	v_lshrrev_b32_e32 v5, 26, v5
	v_ashrrev_i32_e32 v4, 31, v4
	v_add_u32_e32 v5, v0, v5
	v_lshrrev_b32_e32 v4, 26, v4
	v_ashrrev_i32_e32 v5, 6, v5
	v_add_u32_e32 v4, v6, v4
	v_lshlrev_b32_e32 v7, 3, v5
	v_ashrrev_i32_e32 v4, 6, v4
	v_and_b32_e32 v7, -16, v7
	v_add_u32_e32 v7, v4, v7
	v_and_b32_e32 v8, 3, v4
	v_lshrrev_b32_e32 v9, 2, v7
	v_lshlrev_b32_e32 v10, 1, v7
	v_and_or_b32 v8, v7, s0, v8
	v_and_b32_e32 v9, 4, v9
	v_and_b32_e32 v10, 24, v10
	v_or3_b32 v8, v8, v9, v10
	v_mul_i32_i24_e32 v10, 64, v4
	v_sub_u32_e32 v6, v6, v10
	s_ashr_i32 s3, s2, 6
	v_lshlrev_b32_e32 v9, 5, v5
	v_ashrrev_i16_sdwa v6, v173, sext(v6) dst_sel:DWORD dst_unused:UNUSED_PAD src0_sel:DWORD src1_sel:BYTE_0
	s_lshl_b32 s24, s3, 10
	v_and_b32_e32 v9, 32, v9
	v_bfe_i32 v6, v6, 0, 16
	v_add_lshl_u32 v9, v9, v6, 1
	s_add_i32 s25, s24, 0
	v_readlane_b32 s0, v242, 0
	v_lshl_add_u32 v152, v8, 11, v9
	s_add_i32 m0, s25, 0x10000
	v_readlane_b32 s1, v242, 1
	v_lshl_add_u32 v154, v7, 11, v9
	s_add_i32 s26, s25, 0x2000
	s_add_i32 s27, s25, 0x4000
	v_writelane_b32 v241, s28, 58
	s_add_i32 s28, s25, 0x6000
	global_load_lds_dwordx4 v152, s[0:1]
	s_add_i32 m0, s25, 0x12000
	s_ashr_i32 s6, s2, 8
	global_load_lds_dwordx4 v148, s[0:1]
	v_readlane_b32 s0, v243, 58
	s_add_i32 m0, s25, 0x14000
	v_readlane_b32 s1, v243, 59
	s_nop 4
	global_load_lds_dwordx4 v152, s[0:1]
	s_add_i32 m0, s25, 0x16000
	s_cmp_eq_u32 s6, 1
	global_load_lds_dwordx4 v148, s[0:1]
	v_readlane_b32 s0, v243, 60
	s_mov_b32 m0, s25
	v_readlane_b32 s1, v243, 61
	s_nop 4
	global_load_lds_dwordx4 v154, s[0:1]
	s_mov_b32 m0, s26
	s_nop 0
	global_load_lds_dwordx4 v150, s[0:1]
	v_readlane_b32 s0, v243, 62
	s_mov_b32 m0, s27
	v_readlane_b32 s1, v243, 63
	s_nop 4
	global_load_lds_dwordx4 v154, s[0:1]
	s_mov_b32 m0, s28
	s_nop 0
	global_load_lds_dwordx4 v150, s[0:1]
	s_cselect_b64 s[0:1], -1, 0
	s_cmp_lg_u32 s6, 1
	s_cbranch_scc1 .LBB0_94
	s_setprio 1
	s_barrier

; #define PG8_STAGE(bufoff, gbase, voff) do { _Pragma("unroll") for (int _i = 0; _i < 2; ++_i) \
;         __builtin_amdgcn_global_load_lds((const unsigned*)((const char*)(gbase) + (voff)[_i]), (LAS unsigned*)(lds + (bufoff) + ldsw + _i * 8192), 16, 0, 0); } while (0)
; #define PG8_LDA(dst, b, h) do { _Pragma("unroll") for (int m = 0; m < 4; ++m) _Pragma("unroll") for (int k = 0; k < 2; ++k) dst[m][k] = *(const LAS bf16x8*)(lds + PG8_SA(b, h) + aoff + m * 2048 + k * 1024); } while (0)
; #define PG8_LDB(dst, b, h) do { _Pragma("unroll") for (int n = 0; n < 2; ++n) _Pragma("unroll") for (int k = 0; k < 2; ++k) dst[n][k] = *(const LAS bf16x8*)(lds + PG8_SB(b, h) + boff + n * 2048 + k * 1024); } while (0)
; #define PG8_MMA(ai, bj, At, Bt) do { __builtin_amdgcn_s_setprio(1); _Pragma("unroll") for (int m = 0; m < 4; ++m) _Pragma("unroll") for (int n = 0; n < 2; ++n) _Pragma("unroll") for (int k = 0; k < 2; ++k) \
;         acc[ai][bj][m][n] = __builtin_amdgcn_mfma_f32_16x16x32_bf16(Bt[n][k], At[m][k], acc[ai][bj][m][n], 0, 0, 0); __builtin_amdgcn_s_setprio(0); } while (0)
; #define PG8_WAIT_V(n) asm volatile("s_waitcnt vmcnt(" #n ")" ::: "memory")
; #define PG8_WAIT_L(n) asm volatile("s_waitcnt lgkmcnt(" #n ")" ::: "memory")
; #define PG8_BAR __builtin_amdgcn_s_barrier()
; #define PG8_SCHED __builtin_amdgcn_sched_barrier(0)
; template <class Epi>
; DI void gemm_phase(LAS unsigned char* lds, const Gemm g, const Order& S, const Epi& E) {
;     ...
;             PG8_LDB(B0, 0, 0); PG8_LDB(B1, 0, 1); PG8_SCHED; PG8_LDA(At, 0, 0); PG8_STAGE(PG8_SA(1, 1), a1 + hstep, voffA);
;             PG8_WAIT_V(8); PG8_WAIT_L(0); PG8_BAR; PG8_MMA(0, 0, At, B0); PG8_MMA(0, 1, At, B1); PG8_BAR; PG8_SCHED;
;             PG8_LDA(At, 0, 1); PG8_STAGE(PG8_SB(0, 0), b2, voffB); PG8_STAGE(PG8_SB(0, 1), b2 + hstep, voffB); PG8_STAGE(PG8_SA(0, 0), a2, voffA);
;             PG8_WAIT_V(8); PG8_WAIT_L(0); PG8_BAR; PG8_MMA(1, 0, At, B0); PG8_MMA(1, 1, At, B1); PG8_BAR; PG8_SCHED;
.LBB0_107:
	s_add_u32 s20, s2, 0xfffc0080
	s_addc_u32 s21, s3, -1
	s_add_i32 s42, 0, 0x10000
	s_cmp_eq_u32 s41, 12
	s_cselect_b32 s23, s15, s21
	s_cselect_b32 s22, s37, s20
	v_add_u32_e32 v48, s42, v167
	s_cselect_b32 s21, s13, s40
	s_cselect_b32 s20, s38, s39
	s_add_i32 s44, 0, 0x14000
	ds_read_b128 v[132:135], v48
	ds_read_b128 v[160:163], v48 offset:1024
	ds_read_b128 v[178:181], v48 offset:2048
	ds_read_b128 v[182:185], v48 offset:3072
	v_add_u32_e32 v48, s44, v167
	ds_read_b128 v[186:189], v48
	ds_read_b128 v[190:193], v48 offset:1024
	ds_read_b128 v[194:197], v48 offset:2048
	ds_read_b128 v[198:201], v48 offset:3072
	v_lshl_add_u64 v[50:51], s[2:3], 0, v[156:157]
	s_add_i32 m0, s25, 0xc000
	ds_read_b128 v[202:205], v169
	ds_read_b128 v[206:209], v169 offset:1024
	ds_read_b128 v[210:213], v169 offset:2048
	ds_read_b128 v[214:217], v169 offset:3072
	ds_read_b128 v[218:221], v169 offset:4096
	ds_read_b128 v[222:225], v169 offset:5120
	ds_read_b128 v[226:229], v169 offset:6144
	ds_read_b128 v[230:233], v169 offset:7168
	global_load_lds_dwordx4 v[50:51], off
	v_lshl_add_u64 v[50:51], s[2:3], 0, v[158:159]
	s_add_i32 m0, s25, 0xe000
	s_nop 0
	global_load_lds_dwordx4 v[50:51], off
	s_waitcnt vmcnt(8)
	s_waitcnt lgkmcnt(0)
	s_barrier
	s_waitcnt lgkmcnt(0)
	v_mfma_f32_16x16x32_bf16 v[128:131], v[132:135], v[202:205], v[128:131]
	v_mfma_f32_16x16x32_bf16 v[124:127], v[178:181], v[202:205], v[124:127]
	v_mfma_f32_16x16x32_bf16 v[120:123], v[132:135], v[210:213], v[120:123]
	v_mfma_f32_16x16x32_bf16 v[116:119], v[178:181], v[210:213], v[116:119]
	v_mfma_f32_16x16x32_bf16 v[112:115], v[132:135], v[218:221], v[112:115]
	v_mfma_f32_16x16x32_bf16 v[108:111], v[178:181], v[218:221], v[108:111]
	v_mfma_f32_16x16x32_bf16 v[104:107], v[132:135], v[226:229], v[104:107]
	v_mfma_f32_16x16x32_bf16 v[100:103], v[178:181], v[226:229], v[100:103]
	v_mfma_f32_16x16x32_bf16 v[128:131], v[160:163], v[206:209], v[128:131]
	v_mfma_f32_16x16x32_bf16 v[124:127], v[182:185], v[206:209], v[124:127]
	v_mfma_f32_16x16x32_bf16 v[120:123], v[160:163], v[214:217], v[120:123]
	v_mfma_f32_16x16x32_bf16 v[116:119], v[182:185], v[214:217], v[116:119]
	v_mfma_f32_16x16x32_bf16 v[112:115], v[160:163], v[222:225], v[112:115]
	v_mfma_f32_16x16x32_bf16 v[108:111], v[182:185], v[222:225], v[108:111]
	v_mfma_f32_16x16x32_bf16 v[104:107], v[160:163], v[230:233], v[104:107]
	v_mfma_f32_16x16x32_bf16 v[100:103], v[182:185], v[230:233], v[100:103]
	v_mfma_f32_16x16x32_bf16 v[96:99], v[186:189], v[202:205], v[96:99]
	v_mfma_f32_16x16x32_bf16 v[92:95], v[194:197], v[202:205], v[92:95]
	v_mfma_f32_16x16x32_bf16 v[88:91], v[186:189], v[210:213], v[88:91]
	v_mfma_f32_16x16x32_bf16 v[84:87], v[194:197], v[210:213], v[84:87]
	v_mfma_f32_16x16x32_bf16 v[80:83], v[186:189], v[218:221], v[80:83]
	v_mfma_f32_16x16x32_bf16 v[76:79], v[194:197], v[218:221], v[76:79]
	v_mfma_f32_16x16x32_bf16 v[72:75], v[186:189], v[226:229], v[72:75]
	v_mfma_f32_16x16x32_bf16 v[68:71], v[194:197], v[226:229], v[68:71]
	v_mfma_f32_16x16x32_bf16 v[96:99], v[190:193], v[206:209], v[96:99]
	v_mfma_f32_16x16x32_bf16 v[92:95], v[198:201], v[206:209], v[92:95]
	v_mfma_f32_16x16x32_bf16 v[88:91], v[190:193], v[214:217], v[88:91]
	v_mfma_f32_16x16x32_bf16 v[84:87], v[198:201], v[214:217], v[84:87]
	v_mfma_f32_16x16x32_bf16 v[80:83], v[190:193], v[222:225], v[80:83]
	v_mfma_f32_16x16x32_bf16 v[76:79], v[198:201], v[222:225], v[76:79]
	v_mfma_f32_16x16x32_bf16 v[72:75], v[190:193], v[230:233], v[72:75]
	v_mfma_f32_16x16x32_bf16 v[68:71], v[198:201], v[230:233], v[68:71]
	s_barrier
	s_add_i32 s42, s42, s24
	v_lshl_add_u64 v[164:165], s[20:21], 0, v[152:153]
	s_mov_b32 m0, s42
	ds_read_b128 v[202:205], v169 offset:16384
	ds_read_b128 v[206:209], v169 offset:17408
	ds_read_b128 v[210:213], v169 offset:18432
	ds_read_b128 v[214:217], v169 offset:19456
	ds_read_b128 v[218:221], v169 offset:20480
	ds_read_b128 v[222:225], v169 offset:21504
	ds_read_b128 v[226:229], v169 offset:22528
	ds_read_b128 v[230:233], v169 offset:23552
	global_load_lds_dwordx4 v[164:165], off
	s_add_i32 m0, s42, 0x2000
	s_add_u32 s42, s20, 0x40000
	v_lshl_add_u64 v[170:171], s[20:21], 0, v[148:149]
	s_addc_u32 s43, s21, 0
	s_add_i32 s44, s44, s24
	global_load_lds_dwordx4 v[170:171], off
	v_lshl_add_u64 v[50:51], s[42:43], 0, v[152:153]
	s_mov_b32 m0, s44
	v_lshl_add_u64 v[234:235], s[22:23], 0, v[154:155]
	global_load_lds_dwordx4 v[50:51], off
	v_lshl_add_u64 v[50:51], s[42:43], 0, v[148:149]
	s_add_i32 m0, s44, 0x2000
	v_lshl_add_u64 v[236:237], s[22:23], 0, v[150:151]
	global_load_lds_dwordx4 v[50:51], off
	s_mov_b32 m0, s25
	s_nop 0
	global_load_lds_dwordx4 v[234:235], off
	s_mov_b32 m0, s26
	s_nop 0
	global_load_lds_dwordx4 v[236:237], off
	s_waitcnt vmcnt(8)
	s_waitcnt lgkmcnt(0)
	s_barrier
; #define PG8_STAGE(bufoff, gbase, voff) do { _Pragma("unroll") for (int _i = 0; _i < 2; ++_i) \
;         __builtin_amdgcn_global_load_lds((const unsigned*)((const char*)(gbase) + (voff)[_i]), (LAS unsigned*)(lds + (bufoff) + ldsw + _i * 8192), 16, 0, 0); } while (0)
; #define PG8_LDA(dst, b, h) do { _Pragma("unroll") for (int m = 0; m < 4; ++m) _Pragma("unroll") for (int k = 0; k < 2; ++k) dst[m][k] = *(const LAS bf16x8*)(lds + PG8_SA(b, h) + aoff + m * 2048 + k * 1024); } while (0)
; #define PG8_LDB(dst, b, h) do { _Pragma("unroll") for (int n = 0; n < 2; ++n) _Pragma("unroll") for (int k = 0; k < 2; ++k) dst[n][k] = *(const LAS bf16x8*)(lds + PG8_SB(b, h) + boff + n * 2048 + k * 1024); } while (0)
; #define PG8_MMA(ai, bj, At, Bt) do { __builtin_amdgcn_s_setprio(1); _Pragma("unroll") for (int m = 0; m < 4; ++m) _Pragma("unroll") for (int n = 0; n < 2; ++n) _Pragma("unroll") for (int k = 0; k < 2; ++k) \
;         acc[ai][bj][m][n] = __builtin_amdgcn_mfma_f32_16x16x32_bf16(Bt[n][k], At[m][k], acc[ai][bj][m][n], 0, 0, 0); __builtin_amdgcn_s_setprio(0); } while (0)
; #define PG8_WAIT_V(n) asm volatile("s_waitcnt vmcnt(" #n ")" ::: "memory")
; #define PG8_WAIT_L(n) asm volatile("s_waitcnt lgkmcnt(" #n ")" ::: "memory")
; #define PG8_BAR __builtin_amdgcn_s_barrier()
; #define PG8_SCHED __builtin_amdgcn_sched_barrier(0)
; template <class Epi>
; DI void gemm_phase(LAS unsigned char* lds, const Gemm g, const Order& S, const Epi& E) {
;     ...
;             PG8_WAIT_V(8); PG8_WAIT_L(0); PG8_BAR; PG8_MMA(1, 0, At, B0); PG8_MMA(1, 1, At, B1); PG8_BAR; PG8_SCHED;
;             PG8_LDB(B0, 1, 0); PG8_LDB(B1, 1, 1); PG8_SCHED; PG8_LDA(At, 1, 0); PG8_STAGE(PG8_SA(0, 1), a2 + hstep, voffA);
;             PG8_WAIT_V(8); PG8_WAIT_L(0); PG8_BAR; PG8_MMA(0, 0, At, B0); PG8_MMA(0, 1, At, B1); PG8_BAR; PG8_SCHED;
	s_waitcnt lgkmcnt(0)
	v_mfma_f32_16x16x32_bf16 v[64:67], v[132:135], v[202:205], v[64:67]
	v_mfma_f32_16x16x32_bf16 v[60:63], v[178:181], v[202:205], v[60:63]
	v_mfma_f32_16x16x32_bf16 v[56:59], v[132:135], v[210:213], v[56:59]
	v_mfma_f32_16x16x32_bf16 v[50:53], v[178:181], v[210:213], v[52:55]
	v_mfma_f32_16x16x32_bf16 v[44:47], v[132:135], v[218:221], v[44:47]
	v_mfma_f32_16x16x32_bf16 v[40:43], v[178:181], v[218:221], v[40:43]
	v_mfma_f32_16x16x32_bf16 v[36:39], v[132:135], v[226:229], v[36:39]
	v_mfma_f32_16x16x32_bf16 v[32:35], v[178:181], v[226:229], v[32:35]
	v_mfma_f32_16x16x32_bf16 v[64:67], v[160:163], v[206:209], v[64:67]
	v_mfma_f32_16x16x32_bf16 v[60:63], v[182:185], v[206:209], v[60:63]
	v_mfma_f32_16x16x32_bf16 v[56:59], v[160:163], v[214:217], v[56:59]
	v_mfma_f32_16x16x32_bf16 v[50:53], v[182:185], v[214:217], v[50:53]
	v_mfma_f32_16x16x32_bf16 v[44:47], v[160:163], v[222:225], v[44:47]
	v_mfma_f32_16x16x32_bf16 v[40:43], v[182:185], v[222:225], v[40:43]
	v_mfma_f32_16x16x32_bf16 v[36:39], v[160:163], v[230:233], v[36:39]
	v_mfma_f32_16x16x32_bf16 v[32:35], v[182:185], v[230:233], v[32:35]
	v_mfma_f32_16x16x32_bf16 v[28:31], v[186:189], v[202:205], v[28:31]
	v_mfma_f32_16x16x32_bf16 v[24:27], v[194:197], v[202:205], v[24:27]
	v_mfma_f32_16x16x32_bf16 v[20:23], v[186:189], v[210:213], v[20:23]
	v_mfma_f32_16x16x32_bf16 v[16:19], v[194:197], v[210:213], v[16:19]
	v_mfma_f32_16x16x32_bf16 v[12:15], v[186:189], v[218:221], v[12:15]
	v_mfma_f32_16x16x32_bf16 v[8:11], v[194:197], v[218:221], v[8:11]
	v_mfma_f32_16x16x32_bf16 v[4:7], v[186:189], v[226:229], v[4:7]
	v_mfma_f32_16x16x32_bf16 v[0:3], v[194:197], v[226:229], v[0:3]
	v_mfma_f32_16x16x32_bf16 v[28:31], v[190:193], v[206:209], v[28:31]
	v_mfma_f32_16x16x32_bf16 v[24:27], v[198:201], v[206:209], v[24:27]
	v_mfma_f32_16x16x32_bf16 v[20:23], v[190:193], v[214:217], v[20:23]
	v_mfma_f32_16x16x32_bf16 v[16:19], v[198:201], v[214:217], v[16:19]
	v_mfma_f32_16x16x32_bf16 v[12:15], v[190:193], v[222:225], v[12:15]
	v_mfma_f32_16x16x32_bf16 v[8:11], v[198:201], v[222:225], v[8:11]
	v_mfma_f32_16x16x32_bf16 v[4:7], v[190:193], v[230:233], v[4:7]
	v_mfma_f32_16x16x32_bf16 v[0:3], v[198:201], v[230:233], v[0:3]
	s_barrier
	s_add_i32 s42, 0, 0x18000
	v_add_u32_e32 v48, s42, v167
	s_add_i32 s43, 0, 0x1c000
	ds_read_b128 v[132:135], v48
	ds_read_b128 v[160:163], v48 offset:1024
	ds_read_b128 v[178:181], v48 offset:2048
	ds_read_b128 v[182:185], v48 offset:3072
	v_add_u32_e32 v48, s43, v167
	ds_read_b128 v[186:189], v48
	ds_read_b128 v[190:193], v48 offset:1024
	ds_read_b128 v[194:197], v48 offset:2048
	ds_read_b128 v[198:201], v48 offset:3072
	s_add_u32 s22, s22, 0x40000
	s_addc_u32 s23, s23, 0
	s_mov_b32 m0, s27
	v_lshl_add_u64 v[54:55], s[22:23], 0, v[154:155]
	ds_read_b128 v[202:205], v169 offset:32768
	ds_read_b128 v[206:209], v169 offset:33792
	ds_read_b128 v[210:213], v169 offset:34816
	ds_read_b128 v[214:217], v169 offset:35840
	ds_read_b128 v[218:221], v169 offset:36864
	ds_read_b128 v[222:225], v169 offset:37888
	ds_read_b128 v[226:229], v169 offset:38912
	ds_read_b128 v[230:233], v169 offset:39936
	global_load_lds_dwordx4 v[54:55], off
	v_lshl_add_u64 v[54:55], s[22:23], 0, v[150:151]
	s_mov_b32 m0, s28
	s_nop 0
	global_load_lds_dwordx4 v[54:55], off
	s_waitcnt vmcnt(8)
	s_waitcnt lgkmcnt(0)
	s_barrier
	s_waitcnt lgkmcnt(0)
	v_mfma_f32_16x16x32_bf16 v[128:131], v[132:135], v[202:205], v[128:131]
	v_mfma_f32_16x16x32_bf16 v[124:127], v[178:181], v[202:205], v[124:127]
	v_mfma_f32_16x16x32_bf16 v[120:123], v[132:135], v[210:213], v[120:123]
	v_mfma_f32_16x16x32_bf16 v[116:119], v[178:181], v[210:213], v[116:119]
	v_mfma_f32_16x16x32_bf16 v[112:115], v[132:135], v[218:221], v[112:115]
	v_mfma_f32_16x16x32_bf16 v[108:111], v[178:181], v[218:221], v[108:111]
	v_mfma_f32_16x16x32_bf16 v[104:107], v[132:135], v[226:229], v[104:107]
	v_mfma_f32_16x16x32_bf16 v[100:103], v[178:181], v[226:229], v[100:103]
	v_mfma_f32_16x16x32_bf16 v[128:131], v[160:163], v[206:209], v[128:131]
	v_mfma_f32_16x16x32_bf16 v[124:127], v[182:185], v[206:209], v[124:127]
	v_mfma_f32_16x16x32_bf16 v[120:123], v[160:163], v[214:217], v[120:123]
	v_mfma_f32_16x16x32_bf16 v[116:119], v[182:185], v[214:217], v[116:119]
	v_mfma_f32_16x16x32_bf16 v[112:115], v[160:163], v[222:225], v[112:115]
	v_mfma_f32_16x16x32_bf16 v[108:111], v[182:185], v[222:225], v[108:111]
	v_mfma_f32_16x16x32_bf16 v[104:107], v[160:163], v[230:233], v[104:107]
	v_mfma_f32_16x16x32_bf16 v[100:103], v[182:185], v[230:233], v[100:103]
	v_mfma_f32_16x16x32_bf16 v[96:99], v[186:189], v[202:205], v[96:99]
	v_mfma_f32_16x16x32_bf16 v[92:95], v[194:197], v[202:205], v[92:95]
	v_mfma_f32_16x16x32_bf16 v[88:91], v[186:189], v[210:213], v[88:91]
	v_mfma_f32_16x16x32_bf16 v[84:87], v[194:197], v[210:213], v[84:87]
	v_mfma_f32_16x16x32_bf16 v[80:83], v[186:189], v[218:221], v[80:83]
	v_mfma_f32_16x16x32_bf16 v[76:79], v[194:197], v[218:221], v[76:79]
	v_mfma_f32_16x16x32_bf16 v[72:75], v[186:189], v[226:229], v[72:75]
	v_mfma_f32_16x16x32_bf16 v[68:71], v[194:197], v[226:229], v[68:71]
	v_mfma_f32_16x16x32_bf16 v[96:99], v[190:193], v[206:209], v[96:99]
	v_mfma_f32_16x16x32_bf16 v[92:95], v[198:201], v[206:209], v[92:95]
	v_mfma_f32_16x16x32_bf16 v[88:91], v[190:193], v[214:217], v[88:91]
	v_mfma_f32_16x16x32_bf16 v[84:87], v[198:201], v[214:217], v[84:87]
	v_mfma_f32_16x16x32_bf16 v[80:83], v[190:193], v[222:225], v[80:83]
	v_mfma_f32_16x16x32_bf16 v[76:79], v[198:201], v[222:225], v[76:79]
	v_mfma_f32_16x16x32_bf16 v[72:75], v[190:193], v[230:233], v[72:75]
	v_mfma_f32_16x16x32_bf16 v[68:71], v[198:201], v[230:233], v[68:71]
	s_barrier
; #define PG8_STAGE(bufoff, gbase, voff) do { _Pragma("unroll") for (int _i = 0; _i < 2; ++_i) \
;         __builtin_amdgcn_global_load_lds((const unsigned*)((const char*)(gbase) + (voff)[_i]), (LAS unsigned*)(lds + (bufoff) + ldsw + _i * 8192), 16, 0, 0); } while (0)
; #define PG8_LDA(dst, b, h) do { _Pragma("unroll") for (int m = 0; m < 4; ++m) _Pragma("unroll") for (int k = 0; k < 2; ++k) dst[m][k] = *(const LAS bf16x8*)(lds + PG8_SA(b, h) + aoff + m * 2048 + k * 1024); } while (0)
; #define PG8_MMA(ai, bj, At, Bt) do { __builtin_amdgcn_s_setprio(1); _Pragma("unroll") for (int m = 0; m < 4; ++m) _Pragma("unroll") for (int n = 0; n < 2; ++n) _Pragma("unroll") for (int k = 0; k < 2; ++k) \
;         acc[ai][bj][m][n] = __builtin_amdgcn_mfma_f32_16x16x32_bf16(Bt[n][k], At[m][k], acc[ai][bj][m][n], 0, 0, 0); __builtin_amdgcn_s_setprio(0); } while (0)
; #define PG8_WAIT_V(n) asm volatile("s_waitcnt vmcnt(" #n ")" ::: "memory")
; #define PG8_WAIT_L(n) asm volatile("s_waitcnt lgkmcnt(" #n ")" ::: "memory")
; #define PG8_BAR __builtin_amdgcn_s_barrier()
; #define PG8_SCHED __builtin_amdgcn_sched_barrier(0)
; template <class Epi>
; DI void gemm_phase(LAS unsigned char* lds, const Gemm g, const Order& S, const Epi& E) {
;     ...
;             PG8_LDA(At, 1, 1); PG8_STAGE(PG8_SB(1, 0), b3, voffB); PG8_STAGE(PG8_SB(1, 1), b3 + hstep, voffB); PG8_STAGE(PG8_SA(1, 0), a3, voffA);
;             PG8_WAIT_V(8); PG8_WAIT_L(0); PG8_BAR; PG8_MMA(1, 0, At, B0); PG8_MMA(1, 1, At, B1); PG8_BAR; PG8_SCHED;
;         }
;         if (wr == 0) PG8_BAR;
	s_add_i32 s22, s42, s24
	v_lshl_add_u64 v[54:55], v[164:165], 0, s[64:65]
	s_mov_b32 m0, s22
	ds_read_b128 v[202:205], v169 offset:49152
	ds_read_b128 v[206:209], v169 offset:50176
	ds_read_b128 v[210:213], v169 offset:51200
	ds_read_b128 v[214:217], v169 offset:52224
	ds_read_b128 v[218:221], v169 offset:53248
	ds_read_b128 v[222:225], v169 offset:54272
	ds_read_b128 v[226:229], v169 offset:55296
	ds_read_b128 v[230:233], v169 offset:56320
	global_load_lds_dwordx4 v[54:55], off
	s_add_i32 m0, s22, 0x2000
	s_add_u32 s20, s20, 0x40080
	v_lshl_add_u64 v[54:55], v[170:171], 0, s[64:65]
	s_addc_u32 s21, s21, 0
	s_add_i32 s22, s43, s24
	global_load_lds_dwordx4 v[54:55], off
	v_lshl_add_u64 v[54:55], s[20:21], 0, v[152:153]
	s_mov_b32 m0, s22
	s_nop 0
	global_load_lds_dwordx4 v[54:55], off
	v_lshl_add_u64 v[54:55], s[20:21], 0, v[148:149]
	s_add_i32 m0, s22, 0x2000
	s_nop 0
	global_load_lds_dwordx4 v[54:55], off
	v_lshl_add_u64 v[54:55], v[234:235], 0, s[64:65]
	s_mov_b32 m0, s29
	s_nop 0
	global_load_lds_dwordx4 v[54:55], off
	v_lshl_add_u64 v[54:55], v[236:237], 0, s[64:65]
	s_mov_b32 m0, s30
	s_nop 0
	global_load_lds_dwordx4 v[54:55], off
	s_waitcnt vmcnt(8)
	s_waitcnt lgkmcnt(0)
	s_barrier
	s_waitcnt lgkmcnt(0)
	v_mfma_f32_16x16x32_bf16 v[64:67], v[132:135], v[202:205], v[64:67]
	v_mfma_f32_16x16x32_bf16 v[60:63], v[178:181], v[202:205], v[60:63]
	v_mfma_f32_16x16x32_bf16 v[54:57], v[132:135], v[210:213], v[56:59]
	v_mfma_f32_16x16x32_bf16 v[50:53], v[178:181], v[210:213], v[50:53]
	v_mfma_f32_16x16x32_bf16 v[44:47], v[132:135], v[218:221], v[44:47]
	v_mfma_f32_16x16x32_bf16 v[40:43], v[178:181], v[218:221], v[40:43]
	v_mfma_f32_16x16x32_bf16 v[36:39], v[132:135], v[226:229], v[36:39]
	v_mfma_f32_16x16x32_bf16 v[32:35], v[178:181], v[226:229], v[32:35]
	v_mfma_f32_16x16x32_bf16 v[64:67], v[160:163], v[206:209], v[64:67]
	v_mfma_f32_16x16x32_bf16 v[60:63], v[182:185], v[206:209], v[60:63]
	v_mfma_f32_16x16x32_bf16 v[56:59], v[160:163], v[214:217], v[54:57]
	v_mfma_f32_16x16x32_bf16 v[52:55], v[182:185], v[214:217], v[50:53]
	v_mfma_f32_16x16x32_bf16 v[44:47], v[160:163], v[222:225], v[44:47]
	v_mfma_f32_16x16x32_bf16 v[40:43], v[182:185], v[222:225], v[40:43]
	v_mfma_f32_16x16x32_bf16 v[36:39], v[160:163], v[230:233], v[36:39]
	v_mfma_f32_16x16x32_bf16 v[32:35], v[182:185], v[230:233], v[32:35]
	v_mfma_f32_16x16x32_bf16 v[28:31], v[186:189], v[202:205], v[28:31]
	v_mfma_f32_16x16x32_bf16 v[24:27], v[194:197], v[202:205], v[24:27]
	v_mfma_f32_16x16x32_bf16 v[20:23], v[186:189], v[210:213], v[20:23]
	v_mfma_f32_16x16x32_bf16 v[16:19], v[194:197], v[210:213], v[16:19]
	v_mfma_f32_16x16x32_bf16 v[12:15], v[186:189], v[218:221], v[12:15]
	v_mfma_f32_16x16x32_bf16 v[8:11], v[194:197], v[218:221], v[8:11]
	v_mfma_f32_16x16x32_bf16 v[4:7], v[186:189], v[226:229], v[4:7]
	v_mfma_f32_16x16x32_bf16 v[0:3], v[194:197], v[226:229], v[0:3]
	v_mfma_f32_16x16x32_bf16 v[28:31], v[190:193], v[206:209], v[28:31]
	v_mfma_f32_16x16x32_bf16 v[24:27], v[198:201], v[206:209], v[24:27]
	v_mfma_f32_16x16x32_bf16 v[20:23], v[190:193], v[214:217], v[20:23]
	v_mfma_f32_16x16x32_bf16 v[16:19], v[198:201], v[214:217], v[16:19]
	v_mfma_f32_16x16x32_bf16 v[12:15], v[190:193], v[222:225], v[12:15]
	v_mfma_f32_16x16x32_bf16 v[8:11], v[198:201], v[222:225], v[8:11]
	v_mfma_f32_16x16x32_bf16 v[4:7], v[190:193], v[230:233], v[4:7]
	v_mfma_f32_16x16x32_bf16 v[0:3], v[198:201], v[230:233], v[0:3]
	s_barrier
	s_add_i32 s41, s41, 2
	s_add_u32 s2, s2, 0x100
	s_addc_u32 s3, s3, 0
	s_add_u32 s39, s39, 0x100
	s_addc_u32 s40, s40, 0
	s_cmp_gt_u32 s41, 13
	s_cbranch_scc0 .LBB0_107
	s_and_b64 vcc, exec, s[10:11]
	s_cbranch_vccz .LBB0_110
	s_barrier

; #define PG8_WAIT_V(n) asm volatile("s_waitcnt vmcnt(" #n ")" ::: "memory")
; #define PG8_BAR __builtin_amdgcn_s_barrier()
; template <class Epi>
; DI void gemm_phase(LAS unsigned char* lds, const Gemm g, const Order& S, const Epi& E) {
;     ...
;     PG8_WAIT_V(0);
;     PG8_BAR;
.LBB0_119:
	s_setprio 0
	s_waitcnt vmcnt(0)
	v_readlane_b32 s30, v241, 13
	v_readlane_b32 s34, v241, 15
	v_readlane_b32 s29, v241, 12
	v_readlane_b32 s31, v241, 14
	s_movk_i32 s33, 0x3ff
	v_readlane_b32 s35, v241, 16
	v_readlane_b32 s28, v241, 58
	s_barrier

; DI int opaque_tid() { int t = threadIdx.x; asm volatile("" : "+v"(t)); return t; }
; #define PG8_STAGE(bufoff, gbase, voff) do { _Pragma("unroll") for (int _i = 0; _i < 2; ++_i) \
;         __builtin_amdgcn_global_load_lds((const unsigned*)((const char*)(gbase) + (voff)[_i]), (LAS unsigned*)(lds + (bufoff) + ldsw + _i * 8192), 16, 0, 0); } while (0)
; #define PG8_BAR __builtin_amdgcn_s_barrier()
; template <class Epi>
; DI void gemm_phase(LAS unsigned char* lds, const Gemm g, const Order& S, const Epi& E) {
;     const int tid = opaque_tid(), wid = __builtin_amdgcn_readfirstlane(tid >> 6), lane = tid & 63, wr = wid >> 2, wc = wid & 3, fr = lane & 15, fq = lane >> 4;
;     const int K = g.K, nt = K / BK;
;     unsigned voffA[2], voffB[2];
; #pragma unroll
;     for (int i = 0; i < 2; ++i) { int R, C; stage_rc(tid * 16 + i * 8192, R, C); const int Rb = Epi::PERM ? ((R & ~31) + perm32(R & 31)) : R;
;         voffA[i] = (unsigned)(R * K + C) * 2u; voffB[i] = (unsigned)(Rb * K + C) * 2u; }
;     const size_t kstep = (size_t)(BK * 2);
;     const size_t hstep = (size_t)HALF * K * 2;
;     const size_t tstep = 2 * hstep;
;     const unsigned ldsw = (unsigned)wid * 1024u;
;     const int aoff = lds_byte(wr * 64 + fr, fq * 8), boff = lds_byte(wc * 32 + fr, fq * 8);
;     ...
;     Unit cur, nxt; int ui = 0;
;     if (!S.next(0, cur)) return;
;     f32x4 acc[2][2][4][2];
; #pragma unroll
;     for (int a = 0; a < 2; ++a)
; #pragma unroll
;         for (int b = 0; b < 2; ++b)
; #pragma unroll
;             for (int m = 0; m < 4; ++m)
; #pragma unroll
;                 for (int n = 0; n < 2; ++n) acc[a][b][m][n] = (f32x4){0.f, 0.f, 0.f, 0.f};
;     bf16x8 At[4][2], B0[2][2], B1[2][2];
;     const char* cA = (const char*)(cur.sel ? g.A1 : g.A0) + (size_t)cur.pm * tstep; const char* cB = (const char*)(cur.sel ? g.B1 : g.B0) + (size_t)cur.pn * tstep;
;     PG8_STAGE(PG8_SB(0, 0), cB, voffB); PG8_STAGE(PG8_SB(0, 1), cB + hstep, voffB); PG8_STAGE(PG8_SA(0, 0), cA, voffA); PG8_STAGE(PG8_SA(0, 1), cA + hstep, voffA);
;     if (wr == 1) PG8_BAR;
; __global__ void __launch_bounds__(512, 2) mega(Args a) {
;     ...
;         } else {
;             pg8::Gemm g{out9, out9, (const bf16_t*)(ws + WS_WO), (const bf16_t*)(ws + WS_WO), D};
;             pg8::Order S; S.init(M_ALL, D, G, blk, 0);
;             EpiResid E{xin, a.out};
;             pg8::gemm_phase<EpiResid>(lds, g, S, E);
.LBB0_206:
	s_and_b64 vcc, exec, s[36:37]
	s_cbranch_vccz .LBB0_228
	v_readlane_b32 s0, v243, 14
	v_mov_b32_e32 v6, v136
	v_readlane_b32 s1, v243, 15
	s_andn2_b64 vcc, exec, s[0:1]
	v_readfirstlane_b32 s2, v6
	s_cbranch_vccnz .LBB0_227
	v_lshlrev_b32_e32 v4, 4, v6
	v_add_u32_e32 v1, 0x2000, v4
	v_ashrrev_i32_e32 v0, 31, v1
	v_lshrrev_b32_e32 v0, 22, v0
	v_add_u32_e32 v0, v1, v0
	v_ashrrev_i32_e32 v0, 10, v0
	v_lshlrev_b32_e32 v2, 5, v0
	v_and_b32_e32 v3, 32, v2
	v_mul_i32_i24_e32 v2, 0x400, v0
	v_sub_u32_e32 v1, v1, v2
	v_lshrrev_b32_e32 v2, 4, v1
	v_bitop3_b32 v2, v2, v1, 32 bitop3:0x6c
	v_ashrrev_i32_e32 v1, 31, v2
	v_lshrrev_b32_e32 v1, 26, v1
	v_add_u32_e32 v5, v2, v1
	v_ashrrev_i32_e32 v1, 6, v5
	v_and_b32_e32 v5, 0xc0, v5
	v_sub_u32_e32 v2, v2, v5
	v_ashrrev_i16_sdwa v2, v173, sext(v2) dst_sel:DWORD dst_unused:UNUSED_PAD src0_sel:DWORD src1_sel:BYTE_0
	v_lshlrev_b32_e32 v5, 3, v0
	v_bfe_i32 v2, v2, 0, 16
	v_and_b32_e32 v5, 0x1ffff0, v5
	v_add_u32_e32 v3, v3, v2
	v_add_lshl_u32 v5, v1, v5, 11
	v_lshl_add_u32 v130, v3, 1, v5
	v_ashrrev_i32_e32 v3, 31, v6
	v_lshrrev_b32_e32 v3, 26, v3
	v_add_u32_e32 v3, v6, v3
	v_ashrrev_i32_e32 v3, 6, v3
	v_lshlrev_b32_e32 v5, 5, v3
	v_and_b32_e32 v7, 32, v5
	v_bfe_i32 v5, v6, 27, 1
	v_lshrrev_b32_e32 v5, 22, v5
	v_add_u32_e32 v5, v4, v5
	v_and_b32_e32 v5, 0xfffffc00, v5
	v_sub_u32_e32 v4, v4, v5
	v_lshrrev_b32_e32 v5, 4, v4
	v_bitop3_b32 v5, v5, v4, 32 bitop3:0x6c
	v_ashrrev_i32_e32 v4, 31, v4
	v_lshrrev_b32_e32 v4, 26, v4
	v_add_u32_e32 v4, v5, v4
	v_ashrrev_i32_e32 v4, 6, v4
	v_mul_i32_i24_e32 v8, 64, v4
	v_sub_u32_e32 v5, v5, v8
	s_ashr_i32 s3, s2, 6
	v_ashrrev_i16_sdwa v5, v173, sext(v5) dst_sel:DWORD dst_unused:UNUSED_PAD src0_sel:DWORD src1_sel:BYTE_0
	v_lshlrev_b32_e32 v8, 3, v3
	s_lshl_b32 s22, s3, 10
	v_bfe_i32 v5, v5, 0, 16
	v_and_b32_e32 v8, 0x1ffff0, v8
	v_add_u32_e32 v7, v7, v5
	v_add_lshl_u32 v8, v4, v8, 11
	s_add_i32 s23, s22, 0
	v_readlane_b32 s0, v242, 13
	v_lshl_add_u32 v48, v7, 1, v8
	s_add_i32 m0, s23, 0x10000
	v_readlane_b32 s1, v242, 14
	s_add_i32 s24, s23, 0x2000
	s_add_i32 s25, s23, 0x4000
	s_add_i32 s26, s23, 0x6000
	s_ashr_i32 s6, s2, 8
	s_nop 0
	global_load_lds_dwordx4 v48, s[0:1]
	s_add_i32 m0, s23, 0x12000
	s_nop 0
	global_load_lds_dwordx4 v130, s[0:1]
	v_readlane_b32 s0, v242, 7
	s_add_i32 m0, s23, 0x14000
	v_readlane_b32 s1, v242, 8
	s_nop 4
	global_load_lds_dwordx4 v48, s[0:1]
	s_add_i32 m0, s23, 0x16000
	s_cmp_eq_u32 s6, 1
	global_load_lds_dwordx4 v130, s[0:1]
	v_readlane_b32 s0, v242, 9
	s_mov_b32 m0, s23
	v_readlane_b32 s1, v242, 10
	s_nop 4
	global_load_lds_dwordx4 v48, s[0:1]
	s_mov_b32 m0, s24
	s_nop 0
	global_load_lds_dwordx4 v130, s[0:1]
	v_readlane_b32 s0, v242, 11
	s_mov_b32 m0, s25
	v_readlane_b32 s1, v242, 12
	s_nop 4
	global_load_lds_dwordx4 v48, s[0:1]
	s_mov_b32 m0, s26
	s_nop 0
	global_load_lds_dwordx4 v130, s[0:1]
	s_cselect_b64 s[0:1], -1, 0
	s_cmp_lg_u32 s6, 1
	s_cbranch_scc1 .LBB0_210
	s_setprio 1
	s_barrier

; #define PG8_STAGE(bufoff, gbase, voff) do { _Pragma("unroll") for (int _i = 0; _i < 2; ++_i) \
;         __builtin_amdgcn_global_load_lds((const unsigned*)((const char*)(gbase) + (voff)[_i]), (LAS unsigned*)(lds + (bufoff) + ldsw + _i * 8192), 16, 0, 0); } while (0)
; #define PG8_LDA(dst, b, h) do { _Pragma("unroll") for (int m = 0; m < 4; ++m) _Pragma("unroll") for (int k = 0; k < 2; ++k) dst[m][k] = *(const LAS bf16x8*)(lds + PG8_SA(b, h) + aoff + m * 2048 + k * 1024); } while (0)
; #define PG8_LDB(dst, b, h) do { _Pragma("unroll") for (int n = 0; n < 2; ++n) _Pragma("unroll") for (int k = 0; k < 2; ++k) dst[n][k] = *(const LAS bf16x8*)(lds + PG8_SB(b, h) + boff + n * 2048 + k * 1024); } while (0)
; #define PG8_WAIT_V(n) asm volatile("s_waitcnt vmcnt(" #n ")" ::: "memory")
; #define PG8_WAIT_L(n) asm volatile("s_waitcnt lgkmcnt(" #n ")" ::: "memory")
; template <class Epi>
; DI void gemm_phase(LAS unsigned char* lds, const Gemm g, const Order& S, const Epi& E) {
;     ...
;         for (int t = 0; t < nt; t += 2) {
;             const bool last = (t == nt - 2);
;             const char* a1 = cA + (size_t)(t + 1) * kstep;
;             const char* a2 = last ? nA : cA + (size_t)(t + 2) * kstep; const char* b2 = last ? nB : cB + (size_t)(t + 2) * kstep;
;             const char* a3 = a2 + kstep; const char* b3 = b2 + kstep;
;             PG8_LDB(B0, 0, 0); PG8_LDB(B1, 0, 1); PG8_SCHED; PG8_LDA(At, 0, 0); PG8_STAGE(PG8_SA(1, 1), a1 + hstep, voffA);
;             PG8_WAIT_V(8); PG8_WAIT_L(0); PG8_BAR; PG8_MMA(0, 0, At, B0); PG8_MMA(0, 1, At, B1); PG8_BAR; PG8_SCHED;
;             PG8_LDA(At, 0, 1); PG8_STAGE(PG8_SB(0, 0), b2, voffB); PG8_STAGE(PG8_SB(0, 1), b2 + hstep, voffB); PG8_STAGE(PG8_SA(0, 0), a2, voffA);
;             PG8_WAIT_V(8); PG8_WAIT_L(0); PG8_BAR; PG8_MMA(1, 0, At, B0); PG8_MMA(1, 1, At, B1); PG8_BAR; PG8_SCHED;
;             PG8_LDB(B0, 1, 0); PG8_LDB(B1, 1, 1); PG8_SCHED; PG8_LDA(At, 1, 0); PG8_STAGE(PG8_SA(0, 1), a2 + hstep, voffA);
;             PG8_WAIT_V(8); PG8_WAIT_L(0); PG8_BAR; PG8_MMA(0, 0, At, B0); PG8_MMA(0, 1, At, B1); PG8_BAR; PG8_SCHED;
;             PG8_LDA(At, 1, 1); PG8_STAGE(PG8_SB(1, 0), b3, voffB); PG8_STAGE(PG8_SB(1, 1), b3 + hstep, voffB); PG8_STAGE(PG8_SA(1, 0), a3, voffA);
;             PG8_WAIT_V(8); PG8_WAIT_L(0); PG8_BAR; PG8_MMA(1, 0, At, B0); PG8_MMA(1, 1, At, B1); PG8_BAR; PG8_SCHED;
.LBB0_220:
	s_add_u32 s18, s16, 0xfffc0080
	s_addc_u32 s19, s17, -1
	s_add_i32 s38, 0, 0x10000
	s_cmp_eq_u32 s37, 12
	s_cselect_b32 s21, s11, s19
	s_cselect_b32 s20, s33, s18
	v_add_u32_e32 v152, s38, v155
	s_cselect_b32 s19, s9, s36
	s_cselect_b32 s18, s34, s35
	s_add_i32 s40, 0, 0x14000
	ds_read_b128 v[148:151], v152
	ds_read_b128 v[158:161], v152 offset:1024
	ds_read_b128 v[162:165], v152 offset:2048
	ds_read_b128 v[166:169], v152 offset:3072
	v_add_u32_e32 v152, s40, v155
	ds_read_b128 v[178:181], v152
	ds_read_b128 v[182:185], v152 offset:1024
	ds_read_b128 v[186:189], v152 offset:2048
	ds_read_b128 v[190:193], v152 offset:3072
	v_lshl_add_u64 v[152:153], s[16:17], 0, v[132:133]
	s_add_i32 m0, s23, 0xc000
	ds_read_b128 v[194:197], v157
	ds_read_b128 v[198:201], v157 offset:1024
	ds_read_b128 v[202:205], v157 offset:2048
	ds_read_b128 v[206:209], v157 offset:3072
	ds_read_b128 v[210:213], v157 offset:4096
	ds_read_b128 v[214:217], v157 offset:5120
	ds_read_b128 v[218:221], v157 offset:6144
	ds_read_b128 v[222:225], v157 offset:7168
	global_load_lds_dwordx4 v[152:153], off
	v_lshl_add_u64 v[152:153], s[16:17], 0, v[134:135]
	s_add_i32 m0, s23, 0xe000
	s_nop 0
	global_load_lds_dwordx4 v[152:153], off
	s_waitcnt vmcnt(8)
	s_waitcnt lgkmcnt(0)
	s_barrier
	s_waitcnt lgkmcnt(0)
	v_mfma_f32_16x16x32_bf16 v[126:129], v[148:151], v[194:197], v[126:129]
	v_mfma_f32_16x16x32_bf16 v[122:125], v[162:165], v[194:197], v[122:125]
	v_mfma_f32_16x16x32_bf16 v[110:113], v[148:151], v[202:205], v[110:113]
	v_mfma_f32_16x16x32_bf16 v[106:109], v[162:165], v[202:205], v[106:109]
	v_mfma_f32_16x16x32_bf16 v[94:97], v[148:151], v[210:213], v[94:97]
	v_mfma_f32_16x16x32_bf16 v[90:93], v[162:165], v[210:213], v[90:93]
	v_mfma_f32_16x16x32_bf16 v[78:81], v[148:151], v[218:221], v[78:81]
	v_mfma_f32_16x16x32_bf16 v[74:77], v[162:165], v[218:221], v[74:77]
	v_mfma_f32_16x16x32_bf16 v[126:129], v[158:161], v[198:201], v[126:129]
	v_mfma_f32_16x16x32_bf16 v[122:125], v[166:169], v[198:201], v[122:125]
	v_mfma_f32_16x16x32_bf16 v[110:113], v[158:161], v[206:209], v[110:113]
	v_mfma_f32_16x16x32_bf16 v[106:109], v[166:169], v[206:209], v[106:109]
	v_mfma_f32_16x16x32_bf16 v[94:97], v[158:161], v[214:217], v[94:97]
	v_mfma_f32_16x16x32_bf16 v[90:93], v[166:169], v[214:217], v[90:93]
	v_mfma_f32_16x16x32_bf16 v[78:81], v[158:161], v[222:225], v[78:81]
	v_mfma_f32_16x16x32_bf16 v[74:77], v[166:169], v[222:225], v[74:77]
	v_mfma_f32_16x16x32_bf16 v[118:121], v[178:181], v[194:197], v[118:121]
	v_mfma_f32_16x16x32_bf16 v[114:117], v[186:189], v[194:197], v[114:117]
	v_mfma_f32_16x16x32_bf16 v[102:105], v[178:181], v[202:205], v[102:105]
	v_mfma_f32_16x16x32_bf16 v[98:101], v[186:189], v[202:205], v[98:101]
	v_mfma_f32_16x16x32_bf16 v[86:89], v[178:181], v[210:213], v[86:89]
	v_mfma_f32_16x16x32_bf16 v[82:85], v[186:189], v[210:213], v[82:85]
	v_mfma_f32_16x16x32_bf16 v[70:73], v[178:181], v[218:221], v[70:73]
	v_mfma_f32_16x16x32_bf16 v[66:69], v[186:189], v[218:221], v[66:69]
	v_mfma_f32_16x16x32_bf16 v[118:121], v[182:185], v[198:201], v[118:121]
	v_mfma_f32_16x16x32_bf16 v[114:117], v[190:193], v[198:201], v[114:117]
	v_mfma_f32_16x16x32_bf16 v[102:105], v[182:185], v[206:209], v[102:105]
	v_mfma_f32_16x16x32_bf16 v[98:101], v[190:193], v[206:209], v[98:101]
	v_mfma_f32_16x16x32_bf16 v[86:89], v[182:185], v[214:217], v[86:89]
	v_mfma_f32_16x16x32_bf16 v[82:85], v[190:193], v[214:217], v[82:85]
	v_mfma_f32_16x16x32_bf16 v[70:73], v[182:185], v[222:225], v[70:73]
	v_mfma_f32_16x16x32_bf16 v[66:69], v[190:193], v[222:225], v[66:69]
	s_barrier
	s_add_i32 s38, s38, s22
	v_lshl_add_u64 v[152:153], s[18:19], 0, v[48:49]
	s_mov_b32 m0, s38
	ds_read_b128 v[194:197], v157 offset:16384
	ds_read_b128 v[198:201], v157 offset:17408
	ds_read_b128 v[202:205], v157 offset:18432
	ds_read_b128 v[206:209], v157 offset:19456
	ds_read_b128 v[210:213], v157 offset:20480
	ds_read_b128 v[214:217], v157 offset:21504
	ds_read_b128 v[218:221], v157 offset:22528
	ds_read_b128 v[222:225], v157 offset:23552
	global_load_lds_dwordx4 v[152:153], off
	s_add_i32 m0, s38, 0x2000
	s_add_u32 s38, s18, 0x40000
	v_lshl_add_u64 v[170:171], s[18:19], 0, v[130:131]
	s_addc_u32 s39, s19, 0
	s_add_i32 s40, s40, s22
	global_load_lds_dwordx4 v[170:171], off
	v_lshl_add_u64 v[226:227], s[38:39], 0, v[48:49]
	s_mov_b32 m0, s40
	v_lshl_add_u64 v[228:229], s[20:21], 0, v[130:131]
	global_load_lds_dwordx4 v[226:227], off
	v_lshl_add_u64 v[226:227], s[38:39], 0, v[130:131]
	s_add_i32 m0, s40, 0x2000
	s_nop 0
	global_load_lds_dwordx4 v[226:227], off
	v_lshl_add_u64 v[226:227], s[20:21], 0, v[48:49]
	s_mov_b32 m0, s23
	s_nop 0
	global_load_lds_dwordx4 v[226:227], off
	s_mov_b32 m0, s24
	s_nop 0
	global_load_lds_dwordx4 v[228:229], off
	s_waitcnt vmcnt(8)
	s_waitcnt lgkmcnt(0)
	s_barrier
; #define PG8_STAGE(bufoff, gbase, voff) do { _Pragma("unroll") for (int _i = 0; _i < 2; ++_i) \
;         __builtin_amdgcn_global_load_lds((const unsigned*)((const char*)(gbase) + (voff)[_i]), (LAS unsigned*)(lds + (bufoff) + ldsw + _i * 8192), 16, 0, 0); } while (0)
; #define PG8_LDA(dst, b, h) do { _Pragma("unroll") for (int m = 0; m < 4; ++m) _Pragma("unroll") for (int k = 0; k < 2; ++k) dst[m][k] = *(const LAS bf16x8*)(lds + PG8_SA(b, h) + aoff + m * 2048 + k * 1024); } while (0)
; #define PG8_LDB(dst, b, h) do { _Pragma("unroll") for (int n = 0; n < 2; ++n) _Pragma("unroll") for (int k = 0; k < 2; ++k) dst[n][k] = *(const LAS bf16x8*)(lds + PG8_SB(b, h) + boff + n * 2048 + k * 1024); } while (0)
; #define PG8_WAIT_V(n) asm volatile("s_waitcnt vmcnt(" #n ")" ::: "memory")
; #define PG8_WAIT_L(n) asm volatile("s_waitcnt lgkmcnt(" #n ")" ::: "memory")
; template <class Epi>
; DI void gemm_phase(LAS unsigned char* lds, const Gemm g, const Order& S, const Epi& E) {
;     ...
;         for (int t = 0; t < nt; t += 2) {
;             const bool last = (t == nt - 2);
;             const char* a1 = cA + (size_t)(t + 1) * kstep;
;             const char* a2 = last ? nA : cA + (size_t)(t + 2) * kstep; const char* b2 = last ? nB : cB + (size_t)(t + 2) * kstep;
;             const char* a3 = a2 + kstep; const char* b3 = b2 + kstep;
;             PG8_LDB(B0, 0, 0); PG8_LDB(B1, 0, 1); PG8_SCHED; PG8_LDA(At, 0, 0); PG8_STAGE(PG8_SA(1, 1), a1 + hstep, voffA);
;             PG8_WAIT_V(8); PG8_WAIT_L(0); PG8_BAR; PG8_MMA(0, 0, At, B0); PG8_MMA(0, 1, At, B1); PG8_BAR; PG8_SCHED;
;             PG8_LDA(At, 0, 1); PG8_STAGE(PG8_SB(0, 0), b2, voffB); PG8_STAGE(PG8_SB(0, 1), b2 + hstep, voffB); PG8_STAGE(PG8_SA(0, 0), a2, voffA);
;             PG8_WAIT_V(8); PG8_WAIT_L(0); PG8_BAR; PG8_MMA(1, 0, At, B0); PG8_MMA(1, 1, At, B1); PG8_BAR; PG8_SCHED;
;             PG8_LDB(B0, 1, 0); PG8_LDB(B1, 1, 1); PG8_SCHED; PG8_LDA(At, 1, 0); PG8_STAGE(PG8_SA(0, 1), a2 + hstep, voffA);
;             PG8_WAIT_V(8); PG8_WAIT_L(0); PG8_BAR; PG8_MMA(0, 0, At, B0); PG8_MMA(0, 1, At, B1); PG8_BAR; PG8_SCHED;
;             PG8_LDA(At, 1, 1); PG8_STAGE(PG8_SB(1, 0), b3, voffB); PG8_STAGE(PG8_SB(1, 1), b3 + hstep, voffB); PG8_STAGE(PG8_SA(1, 0), a3, voffA);
;             PG8_WAIT_V(8); PG8_WAIT_L(0); PG8_BAR; PG8_MMA(1, 0, At, B0); PG8_MMA(1, 1, At, B1); PG8_BAR; PG8_SCHED;
	s_waitcnt lgkmcnt(0)
	v_mfma_f32_16x16x32_bf16 v[62:65], v[148:151], v[194:197], v[62:65]
	v_mfma_f32_16x16x32_bf16 v[58:61], v[162:165], v[194:197], v[58:61]
	v_mfma_f32_16x16x32_bf16 v[44:47], v[148:151], v[202:205], v[44:47]
	v_mfma_f32_16x16x32_bf16 v[40:43], v[162:165], v[202:205], v[40:43]
	v_mfma_f32_16x16x32_bf16 v[28:31], v[148:151], v[210:213], v[28:31]
	v_mfma_f32_16x16x32_bf16 v[24:27], v[162:165], v[210:213], v[24:27]
	v_mfma_f32_16x16x32_bf16 v[12:15], v[148:151], v[218:221], v[12:15]
	v_mfma_f32_16x16x32_bf16 v[8:11], v[162:165], v[218:221], v[8:11]
	v_mfma_f32_16x16x32_bf16 v[62:65], v[158:161], v[198:201], v[62:65]
	v_mfma_f32_16x16x32_bf16 v[58:61], v[166:169], v[198:201], v[58:61]
	v_mfma_f32_16x16x32_bf16 v[44:47], v[158:161], v[206:209], v[44:47]
	v_mfma_f32_16x16x32_bf16 v[40:43], v[166:169], v[206:209], v[40:43]
	v_mfma_f32_16x16x32_bf16 v[28:31], v[158:161], v[214:217], v[28:31]
	v_mfma_f32_16x16x32_bf16 v[24:27], v[166:169], v[214:217], v[24:27]
	v_mfma_f32_16x16x32_bf16 v[12:15], v[158:161], v[222:225], v[12:15]
	v_mfma_f32_16x16x32_bf16 v[8:11], v[166:169], v[222:225], v[8:11]
	v_mfma_f32_16x16x32_bf16 v[54:57], v[178:181], v[194:197], v[54:57]
	v_mfma_f32_16x16x32_bf16 v[50:53], v[186:189], v[194:197], v[50:53]
	v_mfma_f32_16x16x32_bf16 v[36:39], v[178:181], v[202:205], v[36:39]
	v_mfma_f32_16x16x32_bf16 v[32:35], v[186:189], v[202:205], v[32:35]
	v_mfma_f32_16x16x32_bf16 v[20:23], v[178:181], v[210:213], v[20:23]
	v_mfma_f32_16x16x32_bf16 v[16:19], v[186:189], v[210:213], v[16:19]
	v_mfma_f32_16x16x32_bf16 v[4:7], v[178:181], v[218:221], v[4:7]
	v_mfma_f32_16x16x32_bf16 v[0:3], v[186:189], v[218:221], v[0:3]
	v_mfma_f32_16x16x32_bf16 v[54:57], v[182:185], v[198:201], v[54:57]
	v_mfma_f32_16x16x32_bf16 v[50:53], v[190:193], v[198:201], v[50:53]
	v_mfma_f32_16x16x32_bf16 v[36:39], v[182:185], v[206:209], v[36:39]
	v_mfma_f32_16x16x32_bf16 v[32:35], v[190:193], v[206:209], v[32:35]
	v_mfma_f32_16x16x32_bf16 v[20:23], v[182:185], v[214:217], v[20:23]
	v_mfma_f32_16x16x32_bf16 v[16:19], v[190:193], v[214:217], v[16:19]
	v_mfma_f32_16x16x32_bf16 v[4:7], v[182:185], v[222:225], v[4:7]
	v_mfma_f32_16x16x32_bf16 v[0:3], v[190:193], v[222:225], v[0:3]
	s_barrier
	s_add_i32 s38, 0, 0x18000
	s_add_i32 s39, 0, 0x1c000
	v_add_u32_e32 v166, s38, v155
	v_add_u32_e32 v190, s39, v155
	ds_read_b128 v[148:151], v166
	ds_read_b128 v[158:161], v166 offset:1024
	ds_read_b128 v[162:165], v166 offset:2048
	ds_read_b128 v[166:169], v166 offset:3072
	ds_read_b128 v[178:181], v190
	ds_read_b128 v[182:185], v190 offset:1024
	ds_read_b128 v[186:189], v190 offset:2048
	ds_read_b128 v[190:193], v190 offset:3072
	s_add_u32 s20, s20, 0x40000
	s_addc_u32 s21, s21, 0
	s_mov_b32 m0, s25
	v_lshl_add_u64 v[230:231], s[20:21], 0, v[48:49]
	ds_read_b128 v[194:197], v157 offset:32768
	ds_read_b128 v[198:201], v157 offset:33792
	ds_read_b128 v[202:205], v157 offset:34816
	ds_read_b128 v[206:209], v157 offset:35840
	ds_read_b128 v[210:213], v157 offset:36864
	ds_read_b128 v[214:217], v157 offset:37888
	ds_read_b128 v[218:221], v157 offset:38912
	ds_read_b128 v[222:225], v157 offset:39936
	global_load_lds_dwordx4 v[230:231], off
	v_lshl_add_u64 v[230:231], s[20:21], 0, v[130:131]
	s_mov_b32 m0, s26
	s_nop 0
	global_load_lds_dwordx4 v[230:231], off
	s_waitcnt vmcnt(8)
	s_waitcnt lgkmcnt(0)
	s_barrier
	s_waitcnt lgkmcnt(0)
	v_mfma_f32_16x16x32_bf16 v[126:129], v[148:151], v[194:197], v[126:129]
	v_mfma_f32_16x16x32_bf16 v[122:125], v[162:165], v[194:197], v[122:125]
	v_mfma_f32_16x16x32_bf16 v[110:113], v[148:151], v[202:205], v[110:113]
	v_mfma_f32_16x16x32_bf16 v[106:109], v[162:165], v[202:205], v[106:109]
	v_mfma_f32_16x16x32_bf16 v[94:97], v[148:151], v[210:213], v[94:97]
	v_mfma_f32_16x16x32_bf16 v[90:93], v[162:165], v[210:213], v[90:93]
	v_mfma_f32_16x16x32_bf16 v[78:81], v[148:151], v[218:221], v[78:81]
	v_mfma_f32_16x16x32_bf16 v[74:77], v[162:165], v[218:221], v[74:77]
	v_mfma_f32_16x16x32_bf16 v[126:129], v[158:161], v[198:201], v[126:129]
	v_mfma_f32_16x16x32_bf16 v[122:125], v[166:169], v[198:201], v[122:125]
	v_mfma_f32_16x16x32_bf16 v[110:113], v[158:161], v[206:209], v[110:113]
	v_mfma_f32_16x16x32_bf16 v[106:109], v[166:169], v[206:209], v[106:109]
	v_mfma_f32_16x16x32_bf16 v[94:97], v[158:161], v[214:217], v[94:97]
	v_mfma_f32_16x16x32_bf16 v[90:93], v[166:169], v[214:217], v[90:93]
	v_mfma_f32_16x16x32_bf16 v[78:81], v[158:161], v[222:225], v[78:81]
	v_mfma_f32_16x16x32_bf16 v[74:77], v[166:169], v[222:225], v[74:77]
	v_mfma_f32_16x16x32_bf16 v[118:121], v[178:181], v[194:197], v[118:121]
	v_mfma_f32_16x16x32_bf16 v[114:117], v[186:189], v[194:197], v[114:117]
	v_mfma_f32_16x16x32_bf16 v[102:105], v[178:181], v[202:205], v[102:105]
	v_mfma_f32_16x16x32_bf16 v[98:101], v[186:189], v[202:205], v[98:101]
	v_mfma_f32_16x16x32_bf16 v[86:89], v[178:181], v[210:213], v[86:89]
	v_mfma_f32_16x16x32_bf16 v[82:85], v[186:189], v[210:213], v[82:85]
	v_mfma_f32_16x16x32_bf16 v[70:73], v[178:181], v[218:221], v[70:73]
	v_mfma_f32_16x16x32_bf16 v[66:69], v[186:189], v[218:221], v[66:69]
	v_mfma_f32_16x16x32_bf16 v[118:121], v[182:185], v[198:201], v[118:121]
	v_mfma_f32_16x16x32_bf16 v[114:117], v[190:193], v[198:201], v[114:117]
	v_mfma_f32_16x16x32_bf16 v[102:105], v[182:185], v[206:209], v[102:105]
	v_mfma_f32_16x16x32_bf16 v[98:101], v[190:193], v[206:209], v[98:101]
	v_mfma_f32_16x16x32_bf16 v[86:89], v[182:185], v[214:217], v[86:89]
	v_mfma_f32_16x16x32_bf16 v[82:85], v[190:193], v[214:217], v[82:85]
	v_mfma_f32_16x16x32_bf16 v[70:73], v[182:185], v[222:225], v[70:73]
	v_mfma_f32_16x16x32_bf16 v[66:69], v[190:193], v[222:225], v[66:69]
	s_barrier
; #define PG8_STAGE(bufoff, gbase, voff) do { _Pragma("unroll") for (int _i = 0; _i < 2; ++_i) \
;         __builtin_amdgcn_global_load_lds((const unsigned*)((const char*)(gbase) + (voff)[_i]), (LAS unsigned*)(lds + (bufoff) + ldsw + _i * 8192), 16, 0, 0); } while (0)
; #define PG8_LDA(dst, b, h) do { _Pragma("unroll") for (int m = 0; m < 4; ++m) _Pragma("unroll") for (int k = 0; k < 2; ++k) dst[m][k] = *(const LAS bf16x8*)(lds + PG8_SA(b, h) + aoff + m * 2048 + k * 1024); } while (0)
; #define PG8_LDB(dst, b, h) do { _Pragma("unroll") for (int n = 0; n < 2; ++n) _Pragma("unroll") for (int k = 0; k < 2; ++k) dst[n][k] = *(const LAS bf16x8*)(lds + PG8_SB(b, h) + boff + n * 2048 + k * 1024); } while (0)
; #define PG8_WAIT_V(n) asm volatile("s_waitcnt vmcnt(" #n ")" ::: "memory")
; #define PG8_WAIT_L(n) asm volatile("s_waitcnt lgkmcnt(" #n ")" ::: "memory")
; template <class Epi>
; DI void gemm_phase(LAS unsigned char* lds, const Gemm g, const Order& S, const Epi& E) {
;     ...
;         for (int t = 0; t < nt; t += 2) {
;             const bool last = (t == nt - 2);
;             const char* a1 = cA + (size_t)(t + 1) * kstep;
;             const char* a2 = last ? nA : cA + (size_t)(t + 2) * kstep; const char* b2 = last ? nB : cB + (size_t)(t + 2) * kstep;
;             const char* a3 = a2 + kstep; const char* b3 = b2 + kstep;
;             PG8_LDB(B0, 0, 0); PG8_LDB(B1, 0, 1); PG8_SCHED; PG8_LDA(At, 0, 0); PG8_STAGE(PG8_SA(1, 1), a1 + hstep, voffA);
;             PG8_WAIT_V(8); PG8_WAIT_L(0); PG8_BAR; PG8_MMA(0, 0, At, B0); PG8_MMA(0, 1, At, B1); PG8_BAR; PG8_SCHED;
;             PG8_LDA(At, 0, 1); PG8_STAGE(PG8_SB(0, 0), b2, voffB); PG8_STAGE(PG8_SB(0, 1), b2 + hstep, voffB); PG8_STAGE(PG8_SA(0, 0), a2, voffA);
;             PG8_WAIT_V(8); PG8_WAIT_L(0); PG8_BAR; PG8_MMA(1, 0, At, B0); PG8_MMA(1, 1, At, B1); PG8_BAR; PG8_SCHED;
;             PG8_LDB(B0, 1, 0); PG8_LDB(B1, 1, 1); PG8_SCHED; PG8_LDA(At, 1, 0); PG8_STAGE(PG8_SA(0, 1), a2 + hstep, voffA);
;             PG8_WAIT_V(8); PG8_WAIT_L(0); PG8_BAR; PG8_MMA(0, 0, At, B0); PG8_MMA(0, 1, At, B1); PG8_BAR; PG8_SCHED;
;             PG8_LDA(At, 1, 1); PG8_STAGE(PG8_SB(1, 0), b3, voffB); PG8_STAGE(PG8_SB(1, 1), b3 + hstep, voffB); PG8_STAGE(PG8_SA(1, 0), a3, voffA);
;             PG8_WAIT_V(8); PG8_WAIT_L(0); PG8_BAR; PG8_MMA(1, 0, At, B0); PG8_MMA(1, 1, At, B1); PG8_BAR; PG8_SCHED;
	s_add_i32 s20, s38, s22
	v_lshl_add_u64 v[152:153], v[152:153], 0, s[64:65]
	s_mov_b32 m0, s20
	ds_read_b128 v[194:197], v157 offset:49152
	ds_read_b128 v[198:201], v157 offset:50176
	ds_read_b128 v[202:205], v157 offset:51200
	ds_read_b128 v[206:209], v157 offset:52224
	ds_read_b128 v[210:213], v157 offset:53248
	ds_read_b128 v[214:217], v157 offset:54272
	ds_read_b128 v[218:221], v157 offset:55296
	ds_read_b128 v[222:225], v157 offset:56320
	global_load_lds_dwordx4 v[152:153], off
	s_add_i32 m0, s20, 0x2000
	s_add_u32 s18, s18, 0x40080
	v_lshl_add_u64 v[152:153], v[170:171], 0, s[64:65]
	s_addc_u32 s19, s19, 0
	s_add_i32 s20, s39, s22
	global_load_lds_dwordx4 v[152:153], off
	v_lshl_add_u64 v[152:153], s[18:19], 0, v[48:49]
	s_mov_b32 m0, s20
	s_nop 0
	global_load_lds_dwordx4 v[152:153], off
	v_lshl_add_u64 v[152:153], s[18:19], 0, v[130:131]
	s_add_i32 m0, s20, 0x2000
	s_nop 0
	global_load_lds_dwordx4 v[152:153], off
	v_lshl_add_u64 v[152:153], v[226:227], 0, s[64:65]
	s_mov_b32 m0, s27
	s_nop 0
	global_load_lds_dwordx4 v[152:153], off
	v_lshl_add_u64 v[152:153], v[228:229], 0, s[64:65]
	s_mov_b32 m0, s28
	s_nop 0
	global_load_lds_dwordx4 v[152:153], off
	s_waitcnt vmcnt(8)
	s_waitcnt lgkmcnt(0)
	s_barrier
	s_waitcnt lgkmcnt(0)
	v_mfma_f32_16x16x32_bf16 v[62:65], v[148:151], v[194:197], v[62:65]
	v_mfma_f32_16x16x32_bf16 v[58:61], v[162:165], v[194:197], v[58:61]
	v_mfma_f32_16x16x32_bf16 v[44:47], v[148:151], v[202:205], v[44:47]
	v_mfma_f32_16x16x32_bf16 v[40:43], v[162:165], v[202:205], v[40:43]
	v_mfma_f32_16x16x32_bf16 v[28:31], v[148:151], v[210:213], v[28:31]
	v_mfma_f32_16x16x32_bf16 v[24:27], v[162:165], v[210:213], v[24:27]
	v_mfma_f32_16x16x32_bf16 v[12:15], v[148:151], v[218:221], v[12:15]
	v_mfma_f32_16x16x32_bf16 v[8:11], v[162:165], v[218:221], v[8:11]
	v_mfma_f32_16x16x32_bf16 v[62:65], v[158:161], v[198:201], v[62:65]
	v_mfma_f32_16x16x32_bf16 v[58:61], v[166:169], v[198:201], v[58:61]
	v_mfma_f32_16x16x32_bf16 v[44:47], v[158:161], v[206:209], v[44:47]
	v_mfma_f32_16x16x32_bf16 v[40:43], v[166:169], v[206:209], v[40:43]
	v_mfma_f32_16x16x32_bf16 v[28:31], v[158:161], v[214:217], v[28:31]
	v_mfma_f32_16x16x32_bf16 v[24:27], v[166:169], v[214:217], v[24:27]
	v_mfma_f32_16x16x32_bf16 v[12:15], v[158:161], v[222:225], v[12:15]
	v_mfma_f32_16x16x32_bf16 v[8:11], v[166:169], v[222:225], v[8:11]
	v_mfma_f32_16x16x32_bf16 v[54:57], v[178:181], v[194:197], v[54:57]
	v_mfma_f32_16x16x32_bf16 v[50:53], v[186:189], v[194:197], v[50:53]
	v_mfma_f32_16x16x32_bf16 v[36:39], v[178:181], v[202:205], v[36:39]
	v_mfma_f32_16x16x32_bf16 v[32:35], v[186:189], v[202:205], v[32:35]
	v_mfma_f32_16x16x32_bf16 v[20:23], v[178:181], v[210:213], v[20:23]
	v_mfma_f32_16x16x32_bf16 v[16:19], v[186:189], v[210:213], v[16:19]
	v_mfma_f32_16x16x32_bf16 v[4:7], v[178:181], v[218:221], v[4:7]
	v_mfma_f32_16x16x32_bf16 v[0:3], v[186:189], v[218:221], v[0:3]
	v_mfma_f32_16x16x32_bf16 v[54:57], v[182:185], v[198:201], v[54:57]
	v_mfma_f32_16x16x32_bf16 v[50:53], v[190:193], v[198:201], v[50:53]
	v_mfma_f32_16x16x32_bf16 v[36:39], v[182:185], v[206:209], v[36:39]
	v_mfma_f32_16x16x32_bf16 v[32:35], v[190:193], v[206:209], v[32:35]
	v_mfma_f32_16x16x32_bf16 v[20:23], v[182:185], v[214:217], v[20:23]
	v_mfma_f32_16x16x32_bf16 v[16:19], v[190:193], v[214:217], v[16:19]
	v_mfma_f32_16x16x32_bf16 v[4:7], v[182:185], v[222:225], v[4:7]
	v_mfma_f32_16x16x32_bf16 v[0:3], v[190:193], v[222:225], v[0:3]
	s_barrier
	s_add_i32 s37, s37, 2
	s_add_u32 s16, s16, 0x100
	s_addc_u32 s17, s17, 0
	s_add_u32 s35, s35, 0x100
	s_addc_u32 s36, s36, 0
	s_cmp_gt_u32 s37, 13
	s_cbranch_scc0 .LBB0_220
	v_readlane_b32 s34, v241, 15
	s_and_b64 vcc, exec, s[2:3]
	s_movk_i32 s33, 0x3ff
	v_readlane_b32 s35, v241, 16
	s_cbranch_vccz .LBB0_223
	s_barrier

; #define PG8_WAIT_V(n) asm volatile("s_waitcnt vmcnt(" #n ")" ::: "memory")
; #define PG8_BAR __builtin_amdgcn_s_barrier()
; template <class Epi>
; DI void gemm_phase(LAS unsigned char* lds, const Gemm g, const Order& S, const Epi& E) {
;     ...
;     PG8_WAIT_V(0);
;     PG8_BAR;
.LBB0_226:
	s_setprio 0
	s_waitcnt vmcnt(0)
	v_readlane_b32 s30, v241, 13
	v_readlane_b32 s29, v241, 12
	v_readlane_b32 s31, v241, 14
	s_barrier

; DI int opaque_tid() { int t = threadIdx.x; asm volatile("" : "+v"(t)); return t; }
; #define PG8_STAGE(bufoff, gbase, voff) do { _Pragma("unroll") for (int _i = 0; _i < 2; ++_i) \
;         __builtin_amdgcn_global_load_lds((const unsigned*)((const char*)(gbase) + (voff)[_i]), (LAS unsigned*)(lds + (bufoff) + ldsw + _i * 8192), 16, 0, 0); } while (0)
; #define PG8_WAIT_V(n) asm volatile("s_waitcnt vmcnt(" #n ")" ::: "memory")
; #define PG8_BAR __builtin_amdgcn_s_barrier()
; template <class Epi>
; DI void gemm_phase(LAS unsigned char* lds, const Gemm g, const Order& S, const Epi& E) {
;     const int tid = opaque_tid(), wid = __builtin_amdgcn_readfirstlane(tid >> 6), lane = tid & 63, wr = wid >> 2, wc = wid & 3, fr = lane & 15, fq = lane >> 4;
;     const int K = g.K, nt = K / BK;
;     unsigned voffA[2], voffB[2];
; #pragma unroll
;     for (int i = 0; i < 2; ++i) { int R, C; stage_rc(tid * 16 + i * 8192, R, C); const int Rb = Epi::PERM ? ((R & ~31) + perm32(R & 31)) : R;
;         voffA[i] = (unsigned)(R * K + C) * 2u; voffB[i] = (unsigned)(Rb * K + C) * 2u; }
;     const size_t kstep = (size_t)(BK * 2);
;     const size_t hstep = (size_t)HALF * K * 2;
;     const size_t tstep = 2 * hstep;
;     const unsigned ldsw = (unsigned)wid * 1024u;
;     const int aoff = lds_byte(wr * 64 + fr, fq * 8), boff = lds_byte(wc * 32 + fr, fq * 8);
;     ...
;     Unit cur, nxt; int ui = 0;
;     if (!S.next(0, cur)) return;
;     f32x4 acc[2][2][4][2];
; #pragma unroll
;     for (int a = 0; a < 2; ++a)
; #pragma unroll
;         for (int b = 0; b < 2; ++b)
; #pragma unroll
;             for (int m = 0; m < 4; ++m)
; #pragma unroll
;                 for (int n = 0; n < 2; ++n) acc[a][b][m][n] = (f32x4){0.f, 0.f, 0.f, 0.f};
;     bf16x8 At[4][2], B0[2][2], B1[2][2];
;     const char* cA = (const char*)(cur.sel ? g.A1 : g.A0) + (size_t)cur.pm * tstep; const char* cB = (const char*)(cur.sel ? g.B1 : g.B0) + (size_t)cur.pn * tstep;
;     PG8_STAGE(PG8_SB(0, 0), cB, voffB); PG8_STAGE(PG8_SB(0, 1), cB + hstep, voffB); PG8_STAGE(PG8_SA(0, 0), cA, voffA); PG8_STAGE(PG8_SA(0, 1), cA + hstep, voffA);
;     if (wr == 1) PG8_BAR;
;     PG8_WAIT_V(2); PG8_BAR;
.LBB0_228:
	s_andn2_b64 vcc, exec, s[8:9]
	s_cbranch_vccnz .LBB0_265
	v_readlane_b32 s0, v243, 51
	v_mov_b32_e32 v6, v136
	v_readlane_b32 s1, v243, 52
	s_andn2_b64 vcc, exec, s[0:1]
	v_readfirstlane_b32 s6, v6
	s_cbranch_vccnz .LBB0_265
	v_lshlrev_b32_e32 v0, 4, v6
	v_add_u32_e32 v1, 0x2000, v0
	v_ashrrev_i32_e32 v2, 31, v1
	v_lshrrev_b32_e32 v2, 22, v2
	v_add_u32_e32 v2, v1, v2
	v_ashrrev_i32_e32 v4, 10, v2
	v_mul_i32_i24_e32 v2, 0x400, v4
	v_sub_u32_e32 v1, v1, v2
	v_lshrrev_b32_e32 v2, 4, v1
	v_bitop3_b32 v1, v2, v1, 32 bitop3:0x6c
	v_ashrrev_i32_e32 v2, 31, v1
	v_lshrrev_b32_e32 v2, 26, v2
	v_add_u32_e32 v2, v1, v2
	v_lshlrev_b32_e32 v3, 3, v4
	v_ashrrev_i32_e32 v5, 6, v2
	v_and_b32_e32 v3, -16, v3
	v_add_u32_e32 v3, v5, v3
	v_and_b32_e32 v7, 3, v5
	s_mov_b32 s0, 0x1fffe0
	v_lshrrev_b32_e32 v8, 2, v3
	v_lshlrev_b32_e32 v9, 1, v3
	v_and_b32_e32 v2, 0xc0, v2
	v_and_or_b32 v7, v3, s0, v7
	v_and_b32_e32 v8, 4, v8
	v_and_b32_e32 v9, 24, v9
	v_sub_u32_e32 v1, v1, v2
	v_or3_b32 v8, v7, v8, v9
	v_lshlrev_b32_e32 v7, 5, v4
	v_ashrrev_i16_sdwa v1, v173, sext(v1) dst_sel:DWORD dst_unused:UNUSED_PAD src0_sel:DWORD src1_sel:BYTE_0
	v_and_b32_e32 v9, 32, v7
	v_bfe_i32 v7, v1, 0, 16
	v_add_lshl_u32 v1, v9, v7, 1
	v_lshl_add_u32 v130, v8, 11, v1
	v_lshl_add_u32 v132, v3, 11, v1
	v_bfe_i32 v1, v6, 27, 1
	v_lshrrev_b32_e32 v1, 22, v1
	v_add_u32_e32 v1, v0, v1
	v_and_b32_e32 v1, 0xfffffc00, v1
	v_sub_u32_e32 v0, v0, v1
	v_lshrrev_b32_e32 v1, 4, v0
	v_bitop3_b32 v1, v1, v0, 32 bitop3:0x6c
	v_ashrrev_i32_e32 v0, 31, v0
	v_lshrrev_b32_e32 v0, 26, v0
	v_add_u32_e32 v0, v1, v0
	v_ashrrev_i32_e32 v8, 6, v0
	v_ashrrev_i32_e32 v0, 31, v6
	v_lshrrev_b32_e32 v0, 26, v0
	v_add_u32_e32 v0, v6, v0
	v_ashrrev_i32_e32 v9, 6, v0
	v_lshlrev_b32_e32 v0, 3, v9
	v_and_b32_e32 v0, -16, v0
	v_add_u32_e32 v0, v8, v0
	v_and_b32_e32 v2, 3, v8
	v_lshrrev_b32_e32 v3, 2, v0
	v_lshlrev_b32_e32 v10, 1, v0
	v_and_or_b32 v2, v0, s0, v2
	v_and_b32_e32 v3, 4, v3
	v_and_b32_e32 v10, 24, v10
	v_or3_b32 v2, v2, v3, v10
	v_mul_i32_i24_e32 v10, 64, v8
	v_sub_u32_e32 v1, v1, v10
	s_ashr_i32 s7, s6, 6
	v_lshlrev_b32_e32 v3, 5, v9
	v_ashrrev_i16_sdwa v1, v173, sext(v1) dst_sel:DWORD dst_unused:UNUSED_PAD src0_sel:DWORD src1_sel:BYTE_0
	s_lshl_b32 s26, s7, 10
	v_and_b32_e32 v3, 32, v3
	v_bfe_i32 v10, v1, 0, 16
	v_add_lshl_u32 v1, v3, v10, 1
	s_add_i32 s27, s26, 0
	v_readlane_b32 s0, v242, 30
	v_lshl_add_u32 v134, v2, 11, v1
	s_add_i32 m0, s27, 0x10000
	v_readlane_b32 s1, v242, 31
	s_ashr_i32 s8, s6, 8
	v_readlane_b32 s2, v241, 52
	v_readlane_b32 s3, v241, 53
	v_lshl_add_u32 v148, v0, 11, v1
	v_mov_b32_e32 v149, v49
	global_load_lds_dwordx4 v134, s[0:1]
	s_add_i32 m0, s27, 0x12000
	v_mov_b32_e32 v133, v49
	global_load_lds_dwordx4 v130, s[0:1]
	v_readlane_b32 s0, v242, 28
	s_add_i32 m0, s27, 0x14000
	v_readlane_b32 s1, v242, 29
	s_nop 4
	global_load_lds_dwordx4 v134, s[0:1]
	s_add_i32 m0, s27, 0x16000
	s_nop 0
	global_load_lds_dwordx4 v130, s[0:1]
	v_readlane_b32 s0, v242, 19
	v_readlane_b32 s1, v242, 20
	s_add_u32 s2, s2, s0
	s_addc_u32 s3, s3, s1
	s_add_i32 s28, s27, 0x2000
	s_mov_b32 m0, s27
	s_add_u32 s0, s2, 0x40000
	global_load_lds_dwordx4 v148, s[2:3]
	s_mov_b32 m0, s28
	s_addc_u32 s1, s3, 0
	s_add_i32 s29, s27, 0x4000
	global_load_lds_dwordx4 v132, s[2:3]
	s_mov_b32 m0, s29
	s_add_i32 s30, s27, 0x6000
	global_load_lds_dwordx4 v148, s[0:1]
	s_mov_b32 m0, s30
	s_cmp_eq_u32 s8, 1
	global_load_lds_dwordx4 v132, s[0:1]
	v_lshl_add_u64 v[0:1], s[2:3], 0, v[148:149]
	s_cselect_b64 s[0:1], -1, 0
	s_cmp_lg_u32 s8, 1
	v_lshl_add_u64 v[2:3], s[2:3], 0, v[132:133]
	s_cbranch_scc1 .LBB0_232
	s_setprio 1
	s_barrier

; #define PG8_STAGE(bufoff, gbase, voff) do { _Pragma("unroll") for (int _i = 0; _i < 2; ++_i) \
;         __builtin_amdgcn_global_load_lds((const unsigned*)((const char*)(gbase) + (voff)[_i]), (LAS unsigned*)(lds + (bufoff) + ldsw + _i * 8192), 16, 0, 0); } while (0)
; #define PG8_LDA(dst, b, h) do { _Pragma("unroll") for (int m = 0; m < 4; ++m) _Pragma("unroll") for (int k = 0; k < 2; ++k) dst[m][k] = *(const LAS bf16x8*)(lds + PG8_SA(b, h) + aoff + m * 2048 + k * 1024); } while (0)
; #define PG8_LDB(dst, b, h) do { _Pragma("unroll") for (int n = 0; n < 2; ++n) _Pragma("unroll") for (int k = 0; k < 2; ++k) dst[n][k] = *(const LAS bf16x8*)(lds + PG8_SB(b, h) + boff + n * 2048 + k * 1024); } while (0)
; #define PG8_WAIT_V(n) asm volatile("s_waitcnt vmcnt(" #n ")" ::: "memory")
; #define PG8_WAIT_L(n) asm volatile("s_waitcnt lgkmcnt(" #n ")" ::: "memory")
; template <class Epi>
; DI void gemm_phase(LAS unsigned char* lds, const Gemm g, const Order& S, const Epi& E) {
;     ...
;         for (int t = 0; t < nt; t += 2) {
;             const bool last = (t == nt - 2);
;             const char* a1 = cA + (size_t)(t + 1) * kstep;
;             const char* a2 = last ? nA : cA + (size_t)(t + 2) * kstep; const char* b2 = last ? nB : cB + (size_t)(t + 2) * kstep;
;             const char* a3 = a2 + kstep; const char* b3 = b2 + kstep;
;             PG8_LDB(B0, 0, 0); PG8_LDB(B1, 0, 1); PG8_SCHED; PG8_LDA(At, 0, 0); PG8_STAGE(PG8_SA(1, 1), a1 + hstep, voffA);
;             PG8_WAIT_V(8); PG8_WAIT_L(0); PG8_BAR; PG8_MMA(0, 0, At, B0); PG8_MMA(0, 1, At, B1); PG8_BAR; PG8_SCHED;
;             PG8_LDA(At, 0, 1); PG8_STAGE(PG8_SB(0, 0), b2, voffB); PG8_STAGE(PG8_SB(0, 1), b2 + hstep, voffB); PG8_STAGE(PG8_SA(0, 0), a2, voffA);
;             PG8_WAIT_V(8); PG8_WAIT_L(0); PG8_BAR; PG8_MMA(1, 0, At, B0); PG8_MMA(1, 1, At, B1); PG8_BAR; PG8_SCHED;
;             PG8_LDB(B0, 1, 0); PG8_LDB(B1, 1, 1); PG8_SCHED; PG8_LDA(At, 1, 0); PG8_STAGE(PG8_SA(0, 1), a2 + hstep, voffA);
;             PG8_WAIT_V(8); PG8_WAIT_L(0); PG8_BAR; PG8_MMA(0, 0, At, B0); PG8_MMA(0, 1, At, B1); PG8_BAR; PG8_SCHED;
;             PG8_LDA(At, 1, 1); PG8_STAGE(PG8_SB(1, 0), b3, voffB); PG8_STAGE(PG8_SB(1, 1), b3 + hstep, voffB); PG8_STAGE(PG8_SA(1, 0), a3, voffA);
;             PG8_WAIT_V(8); PG8_WAIT_L(0); PG8_BAR; PG8_MMA(1, 0, At, B0); PG8_MMA(1, 1, At, B1); PG8_BAR; PG8_SCHED;
.LBB0_238:
	s_add_u32 s22, s2, 0xfffc0080
	s_addc_u32 s23, s3, -1
	s_add_i32 s42, 0, 0x10000
	s_cmp_eq_u32 s41, 12
	s_cselect_b32 s25, s17, s23
	s_cselect_b32 s24, s37, s22
	v_add_u32_e32 v48, s42, v165
	s_cselect_b32 s23, s15, s40
	s_cselect_b32 s22, s38, s39
	s_add_i32 s44, 0, 0x14000
	ds_read_b128 v[154:157], v48
	ds_read_b128 v[158:161], v48 offset:1024
	ds_read_b128 v[178:181], v48 offset:2048
	ds_read_b128 v[182:185], v48 offset:3072
	v_add_u32_e32 v48, s44, v165
	ds_read_b128 v[186:189], v48
	ds_read_b128 v[190:193], v48 offset:1024
	ds_read_b128 v[194:197], v48 offset:2048
	ds_read_b128 v[198:201], v48 offset:3072
	v_lshl_add_u64 v[162:163], s[2:3], 0, v[150:151]
	s_add_i32 m0, s27, 0xc000
	ds_read_b128 v[202:205], v169
	ds_read_b128 v[206:209], v169 offset:1024
	ds_read_b128 v[210:213], v169 offset:2048
	ds_read_b128 v[214:217], v169 offset:3072
	ds_read_b128 v[218:221], v169 offset:4096
	ds_read_b128 v[222:225], v169 offset:5120
	ds_read_b128 v[226:229], v169 offset:6144
	ds_read_b128 v[230:233], v169 offset:7168
	global_load_lds_dwordx4 v[162:163], off
	v_lshl_add_u64 v[162:163], s[2:3], 0, v[152:153]
	s_add_i32 m0, s27, 0xe000
	s_nop 0
	global_load_lds_dwordx4 v[162:163], off
	s_waitcnt vmcnt(8)
	s_waitcnt lgkmcnt(0)
	s_barrier
	s_waitcnt lgkmcnt(0)
	v_mfma_f32_16x16x32_bf16 v[126:129], v[154:157], v[202:205], v[126:129]
	v_mfma_f32_16x16x32_bf16 v[118:121], v[178:181], v[202:205], v[118:121]
	v_mfma_f32_16x16x32_bf16 v[110:113], v[154:157], v[210:213], v[110:113]
	v_mfma_f32_16x16x32_bf16 v[102:105], v[178:181], v[210:213], v[102:105]
	v_mfma_f32_16x16x32_bf16 v[94:97], v[154:157], v[218:221], v[94:97]
	v_mfma_f32_16x16x32_bf16 v[86:89], v[178:181], v[218:221], v[86:89]
	v_mfma_f32_16x16x32_bf16 v[78:81], v[154:157], v[226:229], v[78:81]
	v_mfma_f32_16x16x32_bf16 v[70:73], v[178:181], v[226:229], v[70:73]
	v_mfma_f32_16x16x32_bf16 v[126:129], v[158:161], v[206:209], v[126:129]
	v_mfma_f32_16x16x32_bf16 v[118:121], v[182:185], v[206:209], v[118:121]
	v_mfma_f32_16x16x32_bf16 v[110:113], v[158:161], v[214:217], v[110:113]
	v_mfma_f32_16x16x32_bf16 v[102:105], v[182:185], v[214:217], v[102:105]
	v_mfma_f32_16x16x32_bf16 v[94:97], v[158:161], v[222:225], v[94:97]
	v_mfma_f32_16x16x32_bf16 v[86:89], v[182:185], v[222:225], v[86:89]
	v_mfma_f32_16x16x32_bf16 v[78:81], v[158:161], v[230:233], v[78:81]
	v_mfma_f32_16x16x32_bf16 v[70:73], v[182:185], v[230:233], v[70:73]
	v_mfma_f32_16x16x32_bf16 v[122:125], v[186:189], v[202:205], v[122:125]
	v_mfma_f32_16x16x32_bf16 v[114:117], v[194:197], v[202:205], v[114:117]
	v_mfma_f32_16x16x32_bf16 v[106:109], v[186:189], v[210:213], v[106:109]
	v_mfma_f32_16x16x32_bf16 v[98:101], v[194:197], v[210:213], v[98:101]
	v_mfma_f32_16x16x32_bf16 v[90:93], v[186:189], v[218:221], v[90:93]
	v_mfma_f32_16x16x32_bf16 v[82:85], v[194:197], v[218:221], v[82:85]
	v_mfma_f32_16x16x32_bf16 v[74:77], v[186:189], v[226:229], v[74:77]
	v_mfma_f32_16x16x32_bf16 v[66:69], v[194:197], v[226:229], v[66:69]
	v_mfma_f32_16x16x32_bf16 v[122:125], v[190:193], v[206:209], v[122:125]
	v_mfma_f32_16x16x32_bf16 v[114:117], v[198:201], v[206:209], v[114:117]
	v_mfma_f32_16x16x32_bf16 v[106:109], v[190:193], v[214:217], v[106:109]
	v_mfma_f32_16x16x32_bf16 v[98:101], v[198:201], v[214:217], v[98:101]
	v_mfma_f32_16x16x32_bf16 v[90:93], v[190:193], v[222:225], v[90:93]
	v_mfma_f32_16x16x32_bf16 v[82:85], v[198:201], v[222:225], v[82:85]
	v_mfma_f32_16x16x32_bf16 v[74:77], v[190:193], v[230:233], v[74:77]
	v_mfma_f32_16x16x32_bf16 v[66:69], v[198:201], v[230:233], v[66:69]
	s_barrier
	s_add_i32 s42, s42, s26
	v_lshl_add_u64 v[162:163], s[22:23], 0, v[134:135]
	s_mov_b32 m0, s42
	ds_read_b128 v[202:205], v169 offset:16384
	ds_read_b128 v[206:209], v169 offset:17408
	ds_read_b128 v[210:213], v169 offset:18432
	ds_read_b128 v[214:217], v169 offset:19456
	ds_read_b128 v[218:221], v169 offset:20480
	ds_read_b128 v[222:225], v169 offset:21504
	ds_read_b128 v[226:229], v169 offset:22528
	ds_read_b128 v[230:233], v169 offset:23552
	global_load_lds_dwordx4 v[162:163], off
	s_add_i32 m0, s42, 0x2000
	s_add_u32 s42, s22, 0x40000
	v_lshl_add_u64 v[170:171], s[22:23], 0, v[130:131]
	s_addc_u32 s43, s23, 0
	s_add_i32 s44, s44, s26
	global_load_lds_dwordx4 v[170:171], off
	v_lshl_add_u64 v[234:235], s[42:43], 0, v[134:135]
	s_mov_b32 m0, s44
	v_lshl_add_u64 v[236:237], s[24:25], 0, v[132:133]
	global_load_lds_dwordx4 v[234:235], off
	v_lshl_add_u64 v[234:235], s[42:43], 0, v[130:131]
	s_add_i32 m0, s44, 0x2000
	s_nop 0
	global_load_lds_dwordx4 v[234:235], off
	v_lshl_add_u64 v[234:235], s[24:25], 0, v[148:149]
	s_mov_b32 m0, s27
	s_nop 0
	global_load_lds_dwordx4 v[234:235], off
	s_mov_b32 m0, s28
	s_nop 0
	global_load_lds_dwordx4 v[236:237], off
	s_waitcnt vmcnt(8)
	s_waitcnt lgkmcnt(0)
	s_barrier
; #define PG8_STAGE(bufoff, gbase, voff) do { _Pragma("unroll") for (int _i = 0; _i < 2; ++_i) \
;         __builtin_amdgcn_global_load_lds((const unsigned*)((const char*)(gbase) + (voff)[_i]), (LAS unsigned*)(lds + (bufoff) + ldsw + _i * 8192), 16, 0, 0); } while (0)
; #define PG8_LDA(dst, b, h) do { _Pragma("unroll") for (int m = 0; m < 4; ++m) _Pragma("unroll") for (int k = 0; k < 2; ++k) dst[m][k] = *(const LAS bf16x8*)(lds + PG8_SA(b, h) + aoff + m * 2048 + k * 1024); } while (0)
; #define PG8_LDB(dst, b, h) do { _Pragma("unroll") for (int n = 0; n < 2; ++n) _Pragma("unroll") for (int k = 0; k < 2; ++k) dst[n][k] = *(const LAS bf16x8*)(lds + PG8_SB(b, h) + boff + n * 2048 + k * 1024); } while (0)
; #define PG8_WAIT_V(n) asm volatile("s_waitcnt vmcnt(" #n ")" ::: "memory")
; #define PG8_WAIT_L(n) asm volatile("s_waitcnt lgkmcnt(" #n ")" ::: "memory")
; template <class Epi>
; DI void gemm_phase(LAS unsigned char* lds, const Gemm g, const Order& S, const Epi& E) {
;     ...
;         for (int t = 0; t < nt; t += 2) {
;             const bool last = (t == nt - 2);
;             const char* a1 = cA + (size_t)(t + 1) * kstep;
;             const char* a2 = last ? nA : cA + (size_t)(t + 2) * kstep; const char* b2 = last ? nB : cB + (size_t)(t + 2) * kstep;
;             const char* a3 = a2 + kstep; const char* b3 = b2 + kstep;
;             PG8_LDB(B0, 0, 0); PG8_LDB(B1, 0, 1); PG8_SCHED; PG8_LDA(At, 0, 0); PG8_STAGE(PG8_SA(1, 1), a1 + hstep, voffA);
;             PG8_WAIT_V(8); PG8_WAIT_L(0); PG8_BAR; PG8_MMA(0, 0, At, B0); PG8_MMA(0, 1, At, B1); PG8_BAR; PG8_SCHED;
;             PG8_LDA(At, 0, 1); PG8_STAGE(PG8_SB(0, 0), b2, voffB); PG8_STAGE(PG8_SB(0, 1), b2 + hstep, voffB); PG8_STAGE(PG8_SA(0, 0), a2, voffA);
;             PG8_WAIT_V(8); PG8_WAIT_L(0); PG8_BAR; PG8_MMA(1, 0, At, B0); PG8_MMA(1, 1, At, B1); PG8_BAR; PG8_SCHED;
;             PG8_LDB(B0, 1, 0); PG8_LDB(B1, 1, 1); PG8_SCHED; PG8_LDA(At, 1, 0); PG8_STAGE(PG8_SA(0, 1), a2 + hstep, voffA);
;             PG8_WAIT_V(8); PG8_WAIT_L(0); PG8_BAR; PG8_MMA(0, 0, At, B0); PG8_MMA(0, 1, At, B1); PG8_BAR; PG8_SCHED;
;             PG8_LDA(At, 1, 1); PG8_STAGE(PG8_SB(1, 0), b3, voffB); PG8_STAGE(PG8_SB(1, 1), b3 + hstep, voffB); PG8_STAGE(PG8_SA(1, 0), a3, voffA);
;             PG8_WAIT_V(8); PG8_WAIT_L(0); PG8_BAR; PG8_MMA(1, 0, At, B0); PG8_MMA(1, 1, At, B1); PG8_BAR; PG8_SCHED;
	s_waitcnt lgkmcnt(0)
	v_mfma_f32_16x16x32_bf16 v[62:65], v[154:157], v[202:205], v[62:65]
	v_mfma_f32_16x16x32_bf16 v[54:57], v[178:181], v[202:205], v[54:57]
	v_mfma_f32_16x16x32_bf16 v[44:47], v[154:157], v[210:213], v[44:47]
	v_mfma_f32_16x16x32_bf16 v[36:39], v[178:181], v[210:213], v[36:39]
	v_mfma_f32_16x16x32_bf16 v[28:31], v[154:157], v[218:221], v[28:31]
	v_mfma_f32_16x16x32_bf16 v[20:23], v[178:181], v[218:221], v[20:23]
	v_mfma_f32_16x16x32_bf16 v[12:15], v[154:157], v[226:229], v[12:15]
	v_mfma_f32_16x16x32_bf16 v[4:7], v[178:181], v[226:229], v[4:7]
	v_mfma_f32_16x16x32_bf16 v[62:65], v[158:161], v[206:209], v[62:65]
	v_mfma_f32_16x16x32_bf16 v[54:57], v[182:185], v[206:209], v[54:57]
	v_mfma_f32_16x16x32_bf16 v[44:47], v[158:161], v[214:217], v[44:47]
	v_mfma_f32_16x16x32_bf16 v[36:39], v[182:185], v[214:217], v[36:39]
	v_mfma_f32_16x16x32_bf16 v[28:31], v[158:161], v[222:225], v[28:31]
	v_mfma_f32_16x16x32_bf16 v[20:23], v[182:185], v[222:225], v[20:23]
	v_mfma_f32_16x16x32_bf16 v[12:15], v[158:161], v[230:233], v[12:15]
	v_mfma_f32_16x16x32_bf16 v[4:7], v[182:185], v[230:233], v[4:7]
	v_mfma_f32_16x16x32_bf16 v[58:61], v[186:189], v[202:205], v[58:61]
	v_mfma_f32_16x16x32_bf16 v[50:53], v[194:197], v[202:205], v[50:53]
	v_mfma_f32_16x16x32_bf16 v[40:43], v[186:189], v[210:213], v[40:43]
	v_mfma_f32_16x16x32_bf16 v[32:35], v[194:197], v[210:213], v[32:35]
	v_mfma_f32_16x16x32_bf16 v[24:27], v[186:189], v[218:221], v[24:27]
	v_mfma_f32_16x16x32_bf16 v[16:19], v[194:197], v[218:221], v[16:19]
	v_mfma_f32_16x16x32_bf16 v[8:11], v[186:189], v[226:229], v[8:11]
	v_mfma_f32_16x16x32_bf16 v[0:3], v[194:197], v[226:229], v[0:3]
	v_mfma_f32_16x16x32_bf16 v[58:61], v[190:193], v[206:209], v[58:61]
	v_mfma_f32_16x16x32_bf16 v[50:53], v[198:201], v[206:209], v[50:53]
	v_mfma_f32_16x16x32_bf16 v[40:43], v[190:193], v[214:217], v[40:43]
	v_mfma_f32_16x16x32_bf16 v[32:35], v[198:201], v[214:217], v[32:35]
	v_mfma_f32_16x16x32_bf16 v[24:27], v[190:193], v[222:225], v[24:27]
	v_mfma_f32_16x16x32_bf16 v[16:19], v[198:201], v[222:225], v[16:19]
	v_mfma_f32_16x16x32_bf16 v[8:11], v[190:193], v[230:233], v[8:11]
	v_mfma_f32_16x16x32_bf16 v[0:3], v[198:201], v[230:233], v[0:3]
	s_barrier
	s_add_i32 s42, 0, 0x18000
	v_add_u32_e32 v48, s42, v165
	s_add_i32 s43, 0, 0x1c000
	ds_read_b128 v[154:157], v48
	ds_read_b128 v[158:161], v48 offset:1024
	ds_read_b128 v[178:181], v48 offset:2048
	ds_read_b128 v[182:185], v48 offset:3072
	v_add_u32_e32 v48, s43, v165
	ds_read_b128 v[186:189], v48
	ds_read_b128 v[190:193], v48 offset:1024
	ds_read_b128 v[194:197], v48 offset:2048
	ds_read_b128 v[198:201], v48 offset:3072
	s_add_u32 s24, s24, 0x40000
	s_addc_u32 s25, s25, 0
	s_mov_b32 m0, s29
	v_lshl_add_u64 v[238:239], s[24:25], 0, v[148:149]
	ds_read_b128 v[202:205], v169 offset:32768
	ds_read_b128 v[206:209], v169 offset:33792
	ds_read_b128 v[210:213], v169 offset:34816
	ds_read_b128 v[214:217], v169 offset:35840
	ds_read_b128 v[218:221], v169 offset:36864
	ds_read_b128 v[222:225], v169 offset:37888
	ds_read_b128 v[226:229], v169 offset:38912
	ds_read_b128 v[230:233], v169 offset:39936
	global_load_lds_dwordx4 v[238:239], off
	v_lshl_add_u64 v[238:239], s[24:25], 0, v[132:133]
	s_mov_b32 m0, s30
	s_nop 0
	global_load_lds_dwordx4 v[238:239], off
	s_waitcnt vmcnt(8)
	s_waitcnt lgkmcnt(0)
	s_barrier
	s_waitcnt lgkmcnt(0)
	v_mfma_f32_16x16x32_bf16 v[126:129], v[154:157], v[202:205], v[126:129]
	v_mfma_f32_16x16x32_bf16 v[118:121], v[178:181], v[202:205], v[118:121]
	v_mfma_f32_16x16x32_bf16 v[110:113], v[154:157], v[210:213], v[110:113]
	v_mfma_f32_16x16x32_bf16 v[102:105], v[178:181], v[210:213], v[102:105]
	v_mfma_f32_16x16x32_bf16 v[94:97], v[154:157], v[218:221], v[94:97]
	v_mfma_f32_16x16x32_bf16 v[86:89], v[178:181], v[218:221], v[86:89]
	v_mfma_f32_16x16x32_bf16 v[78:81], v[154:157], v[226:229], v[78:81]
	v_mfma_f32_16x16x32_bf16 v[70:73], v[178:181], v[226:229], v[70:73]
	v_mfma_f32_16x16x32_bf16 v[126:129], v[158:161], v[206:209], v[126:129]
	v_mfma_f32_16x16x32_bf16 v[118:121], v[182:185], v[206:209], v[118:121]
	v_mfma_f32_16x16x32_bf16 v[110:113], v[158:161], v[214:217], v[110:113]
	v_mfma_f32_16x16x32_bf16 v[102:105], v[182:185], v[214:217], v[102:105]
	v_mfma_f32_16x16x32_bf16 v[94:97], v[158:161], v[222:225], v[94:97]
	v_mfma_f32_16x16x32_bf16 v[86:89], v[182:185], v[222:225], v[86:89]
	v_mfma_f32_16x16x32_bf16 v[78:81], v[158:161], v[230:233], v[78:81]
	v_mfma_f32_16x16x32_bf16 v[70:73], v[182:185], v[230:233], v[70:73]
	v_mfma_f32_16x16x32_bf16 v[122:125], v[186:189], v[202:205], v[122:125]
	v_mfma_f32_16x16x32_bf16 v[114:117], v[194:197], v[202:205], v[114:117]
	v_mfma_f32_16x16x32_bf16 v[106:109], v[186:189], v[210:213], v[106:109]
	v_mfma_f32_16x16x32_bf16 v[98:101], v[194:197], v[210:213], v[98:101]
	v_mfma_f32_16x16x32_bf16 v[90:93], v[186:189], v[218:221], v[90:93]
	v_mfma_f32_16x16x32_bf16 v[82:85], v[194:197], v[218:221], v[82:85]
	v_mfma_f32_16x16x32_bf16 v[74:77], v[186:189], v[226:229], v[74:77]
	v_mfma_f32_16x16x32_bf16 v[66:69], v[194:197], v[226:229], v[66:69]
	v_mfma_f32_16x16x32_bf16 v[122:125], v[190:193], v[206:209], v[122:125]
	v_mfma_f32_16x16x32_bf16 v[114:117], v[198:201], v[206:209], v[114:117]
	v_mfma_f32_16x16x32_bf16 v[106:109], v[190:193], v[214:217], v[106:109]
	v_mfma_f32_16x16x32_bf16 v[98:101], v[198:201], v[214:217], v[98:101]
	v_mfma_f32_16x16x32_bf16 v[90:93], v[190:193], v[222:225], v[90:93]
	v_mfma_f32_16x16x32_bf16 v[82:85], v[198:201], v[222:225], v[82:85]
	v_mfma_f32_16x16x32_bf16 v[74:77], v[190:193], v[230:233], v[74:77]
	v_mfma_f32_16x16x32_bf16 v[66:69], v[198:201], v[230:233], v[66:69]
	s_barrier
; #define PG8_STAGE(bufoff, gbase, voff) do { _Pragma("unroll") for (int _i = 0; _i < 2; ++_i) \
;         __builtin_amdgcn_global_load_lds((const unsigned*)((const char*)(gbase) + (voff)[_i]), (LAS unsigned*)(lds + (bufoff) + ldsw + _i * 8192), 16, 0, 0); } while (0)
; #define PG8_LDA(dst, b, h) do { _Pragma("unroll") for (int m = 0; m < 4; ++m) _Pragma("unroll") for (int k = 0; k < 2; ++k) dst[m][k] = *(const LAS bf16x8*)(lds + PG8_SA(b, h) + aoff + m * 2048 + k * 1024); } while (0)
; #define PG8_LDB(dst, b, h) do { _Pragma("unroll") for (int n = 0; n < 2; ++n) _Pragma("unroll") for (int k = 0; k < 2; ++k) dst[n][k] = *(const LAS bf16x8*)(lds + PG8_SB(b, h) + boff + n * 2048 + k * 1024); } while (0)
; #define PG8_WAIT_V(n) asm volatile("s_waitcnt vmcnt(" #n ")" ::: "memory")
; #define PG8_WAIT_L(n) asm volatile("s_waitcnt lgkmcnt(" #n ")" ::: "memory")
; template <class Epi>
; DI void gemm_phase(LAS unsigned char* lds, const Gemm g, const Order& S, const Epi& E) {
;     ...
;         for (int t = 0; t < nt; t += 2) {
;             const bool last = (t == nt - 2);
;             const char* a1 = cA + (size_t)(t + 1) * kstep;
;             const char* a2 = last ? nA : cA + (size_t)(t + 2) * kstep; const char* b2 = last ? nB : cB + (size_t)(t + 2) * kstep;
;             const char* a3 = a2 + kstep; const char* b3 = b2 + kstep;
;             PG8_LDB(B0, 0, 0); PG8_LDB(B1, 0, 1); PG8_SCHED; PG8_LDA(At, 0, 0); PG8_STAGE(PG8_SA(1, 1), a1 + hstep, voffA);
;             PG8_WAIT_V(8); PG8_WAIT_L(0); PG8_BAR; PG8_MMA(0, 0, At, B0); PG8_MMA(0, 1, At, B1); PG8_BAR; PG8_SCHED;
;             PG8_LDA(At, 0, 1); PG8_STAGE(PG8_SB(0, 0), b2, voffB); PG8_STAGE(PG8_SB(0, 1), b2 + hstep, voffB); PG8_STAGE(PG8_SA(0, 0), a2, voffA);
;             PG8_WAIT_V(8); PG8_WAIT_L(0); PG8_BAR; PG8_MMA(1, 0, At, B0); PG8_MMA(1, 1, At, B1); PG8_BAR; PG8_SCHED;
;             PG8_LDB(B0, 1, 0); PG8_LDB(B1, 1, 1); PG8_SCHED; PG8_LDA(At, 1, 0); PG8_STAGE(PG8_SA(0, 1), a2 + hstep, voffA);
;             PG8_WAIT_V(8); PG8_WAIT_L(0); PG8_BAR; PG8_MMA(0, 0, At, B0); PG8_MMA(0, 1, At, B1); PG8_BAR; PG8_SCHED;
;             PG8_LDA(At, 1, 1); PG8_STAGE(PG8_SB(1, 0), b3, voffB); PG8_STAGE(PG8_SB(1, 1), b3 + hstep, voffB); PG8_STAGE(PG8_SA(1, 0), a3, voffA);
;             PG8_WAIT_V(8); PG8_WAIT_L(0); PG8_BAR; PG8_MMA(1, 0, At, B0); PG8_MMA(1, 1, At, B1); PG8_BAR; PG8_SCHED;
	s_add_i32 s24, s42, s26
	v_lshl_add_u64 v[162:163], v[162:163], 0, s[64:65]
	s_mov_b32 m0, s24
	ds_read_b128 v[202:205], v169 offset:49152
	ds_read_b128 v[206:209], v169 offset:50176
	ds_read_b128 v[210:213], v169 offset:51200
	ds_read_b128 v[214:217], v169 offset:52224
	ds_read_b128 v[218:221], v169 offset:53248
	ds_read_b128 v[222:225], v169 offset:54272
	ds_read_b128 v[226:229], v169 offset:55296
	ds_read_b128 v[230:233], v169 offset:56320
	global_load_lds_dwordx4 v[162:163], off
	s_add_i32 m0, s24, 0x2000
	s_add_u32 s22, s22, 0x40080
	v_lshl_add_u64 v[162:163], v[170:171], 0, s[64:65]
	s_addc_u32 s23, s23, 0
	s_add_i32 s24, s43, s26
	global_load_lds_dwordx4 v[162:163], off
	v_lshl_add_u64 v[162:163], s[22:23], 0, v[134:135]
	s_mov_b32 m0, s24
	s_nop 0
	global_load_lds_dwordx4 v[162:163], off
	v_lshl_add_u64 v[162:163], s[22:23], 0, v[130:131]
	s_add_i32 m0, s24, 0x2000
	s_nop 0
	global_load_lds_dwordx4 v[162:163], off
	v_lshl_add_u64 v[162:163], v[234:235], 0, s[64:65]
	s_mov_b32 m0, s31
	s_nop 0
	global_load_lds_dwordx4 v[162:163], off
	v_lshl_add_u64 v[162:163], v[236:237], 0, s[64:65]
	s_mov_b32 m0, s34
	s_nop 0
	global_load_lds_dwordx4 v[162:163], off
	s_waitcnt vmcnt(8)
	s_waitcnt lgkmcnt(0)
	s_barrier
	s_waitcnt lgkmcnt(0)
	v_mfma_f32_16x16x32_bf16 v[62:65], v[154:157], v[202:205], v[62:65]
	v_mfma_f32_16x16x32_bf16 v[54:57], v[178:181], v[202:205], v[54:57]
	v_mfma_f32_16x16x32_bf16 v[44:47], v[154:157], v[210:213], v[44:47]
	v_mfma_f32_16x16x32_bf16 v[36:39], v[178:181], v[210:213], v[36:39]
	v_mfma_f32_16x16x32_bf16 v[28:31], v[154:157], v[218:221], v[28:31]
	v_mfma_f32_16x16x32_bf16 v[20:23], v[178:181], v[218:221], v[20:23]
	v_mfma_f32_16x16x32_bf16 v[12:15], v[154:157], v[226:229], v[12:15]
	v_mfma_f32_16x16x32_bf16 v[4:7], v[178:181], v[226:229], v[4:7]
	v_mfma_f32_16x16x32_bf16 v[62:65], v[158:161], v[206:209], v[62:65]
	v_mfma_f32_16x16x32_bf16 v[54:57], v[182:185], v[206:209], v[54:57]
	v_mfma_f32_16x16x32_bf16 v[44:47], v[158:161], v[214:217], v[44:47]
	v_mfma_f32_16x16x32_bf16 v[36:39], v[182:185], v[214:217], v[36:39]
	v_mfma_f32_16x16x32_bf16 v[28:31], v[158:161], v[222:225], v[28:31]
	v_mfma_f32_16x16x32_bf16 v[20:23], v[182:185], v[222:225], v[20:23]
	v_mfma_f32_16x16x32_bf16 v[12:15], v[158:161], v[230:233], v[12:15]
	v_mfma_f32_16x16x32_bf16 v[4:7], v[182:185], v[230:233], v[4:7]
	v_mfma_f32_16x16x32_bf16 v[58:61], v[186:189], v[202:205], v[58:61]
	v_mfma_f32_16x16x32_bf16 v[50:53], v[194:197], v[202:205], v[50:53]
	v_mfma_f32_16x16x32_bf16 v[40:43], v[186:189], v[210:213], v[40:43]
	v_mfma_f32_16x16x32_bf16 v[32:35], v[194:197], v[210:213], v[32:35]
	v_mfma_f32_16x16x32_bf16 v[24:27], v[186:189], v[218:221], v[24:27]
	v_mfma_f32_16x16x32_bf16 v[16:19], v[194:197], v[218:221], v[16:19]
	v_mfma_f32_16x16x32_bf16 v[8:11], v[186:189], v[226:229], v[8:11]
	v_mfma_f32_16x16x32_bf16 v[0:3], v[194:197], v[226:229], v[0:3]
	v_mfma_f32_16x16x32_bf16 v[58:61], v[190:193], v[206:209], v[58:61]
	v_mfma_f32_16x16x32_bf16 v[50:53], v[198:201], v[206:209], v[50:53]
	v_mfma_f32_16x16x32_bf16 v[40:43], v[190:193], v[214:217], v[40:43]
	v_mfma_f32_16x16x32_bf16 v[32:35], v[198:201], v[214:217], v[32:35]
	v_mfma_f32_16x16x32_bf16 v[24:27], v[190:193], v[222:225], v[24:27]
	v_mfma_f32_16x16x32_bf16 v[16:19], v[198:201], v[222:225], v[16:19]
	v_mfma_f32_16x16x32_bf16 v[8:11], v[190:193], v[230:233], v[8:11]
	v_mfma_f32_16x16x32_bf16 v[0:3], v[198:201], v[230:233], v[0:3]
	s_barrier
	s_add_i32 s41, s41, 2
	s_add_u32 s2, s2, 0x100
	s_addc_u32 s3, s3, 0
	s_add_u32 s39, s39, 0x100
	s_addc_u32 s40, s40, 0
	s_cmp_gt_u32 s41, 13
	s_cbranch_scc0 .LBB0_238
	s_and_b64 vcc, exec, s[8:9]
	s_cbranch_vccz .LBB0_241
	s_barrier

; #define PG8_WAIT_V(n) asm volatile("s_waitcnt vmcnt(" #n ")" ::: "memory")
; #define PG8_BAR __builtin_amdgcn_s_barrier()
; template <class Epi>
; DI void gemm_phase(LAS unsigned char* lds, const Gemm g, const Order& S, const Epi& E) {
;     ...
;     PG8_WAIT_V(0);
;     PG8_BAR;
.LBB0_264:
	s_setprio 0
	s_waitcnt vmcnt(0)
	v_readlane_b32 s30, v241, 13
	v_readlane_b32 s34, v241, 15
	v_readlane_b32 s29, v241, 12
	v_readlane_b32 s31, v241, 14
	s_movk_i32 s33, 0x3ff
	v_readlane_b32 s35, v241, 16
	s_barrier
